# GEMM epilogue dwordx4 stores of U / X1H / XH / H made write-through (sc1) so the grid barrier L2 write-back has less to flush
# speedup vs baseline: 1.0013x; 1.0013x over previous
; __device__ __forceinline__ u32x4 pack8(f32x4 a, f32x4 b) { u32x4 w; w.x = cvtpk(a[0], a[1]); w.y = cvtpk(a[2], a[3]); w.z = cvtpk(b[0], b[1]); w.w = cvtpk(b[2], b[3]); return w; }
;     __device__ __forceinline__ void fused(AccT& acc, const Unit& u, int wr, int wc, int fr, int fq, LAS unsigned char* lx, int tid) const {
;     ...
;         f32x4 gv[2][2], bv[2][2];
; #pragma unroll
;         for (int bj = 0; bj < 2; ++bj)
; #pragma unroll
;             for (int n = 0; n < 2; ++n) { gv[bj][n] = *(const f32x4*)(g + EPI_COL(u, bj) + 4 * n); bv[bj][n] = *(const f32x4*)(b + EPI_COL(u, bj) + 4 * n); }
; #pragma unroll
;         for (int ai = 0; ai < 2; ++ai)
; #pragma unroll
;             for (int m = 0; m < 4; ++m) {
;                 const int row = EPI_ROW(u, ai, m); const f32x2 st = Sx[ai * 128 + wr * 64 + m * 16 + fr];
; #pragma unroll
;                 for (int bj = 0; bj < 2; ++bj) {
;                     const size_t off = (size_t)row * DM + EPI_COL(u, bj);
;                     const f32x4 y0 = (acc[ai][bj][m][0] - st.x) * st.y * gv[bj][0] + bv[bj][0], y1 = (acc[ai][bj][m][1] - st.x) * st.y * gv[bj][1] + bv[bj][1];
;                     if (F32OUT) { *(f32x4*)(o32 + off) = y0; *(f32x4*)(o32 + off + 4) = y1; }
;                     else *(u32x4*)(o16 + off) = pack8(y0, y1);
;                 }
.LBB0_118:
	s_or_b64 exec, exec, s[10:11]
	v_lshlrev_b64 v[2:3], 2, v[140:141]
	s_waitcnt lgkmcnt(0)
	s_barrier
	s_waitcnt lgkmcnt(0)
	v_lshl_add_u64 v[4:5], s[44:45], 0, v[2:3]
	v_lshl_add_u64 v[6:7], s[46:47], 0, v[2:3]
	flat_load_dwordx4 v[26:29], v[6:7]
	flat_load_dwordx4 v[30:33], v[4:5]
	flat_load_dwordx4 v[18:21], v[4:5] offset:16
	flat_load_dwordx4 v[22:25], v[6:7] offset:16
	flat_load_dwordx4 v[10:13], v[6:7] offset:512
	flat_load_dwordx4 v[14:17], v[4:5] offset:512
	s_nop 0
	flat_load_dwordx4 v[2:5], v[4:5] offset:528
	s_nop 0
	flat_load_dwordx4 v[6:9], v[6:7] offset:528
	v_lshlrev_b32_e32 v35, 3, v238
	s_add_i32 s0, 0, 0x22000
	v_lshlrev_b32_e32 v37, 3, v229
	v_add3_u32 v35, s0, v35, v37
	ds_read_b64 v[218:219], v35
	v_readlane_b32 s0, v255, 0
	v_readlane_b32 s1, v255, 1
	v_lshlrev_b64 v[140:141], 1, v[140:141]
	s_and_b64 vcc, exec, s[6:7]
	s_waitcnt lgkmcnt(0)
	v_sub_f32_e32 v115, v114, v218
	v_sub_f32_e32 v114, v148, v218
	v_sub_f32_e32 v123, v122, v218
	v_sub_f32_e32 v122, v144, v218
	v_sub_f32_e32 v117, v116, v218
	v_sub_f32_e32 v116, v150, v218
	v_sub_f32_e32 v119, v118, v218
	v_sub_f32_e32 v118, v146, v218
	v_sub_f32_e32 v151, v151, v218
	v_sub_f32_e32 v150, v147, v218
	v_sub_f32_e32 v147, v149, v218
	v_sub_f32_e32 v146, v145, v218
	v_sub_f32_e32 v129, v129, v218
	v_sub_f32_e32 v128, v128, v218
	v_sub_f32_e32 v127, v127, v218
	v_sub_f32_e32 v126, v126, v218
	v_pk_mul_f32 v[122:123], v[218:219], v[122:123] op_sel:[1,0]
	v_pk_mul_f32 v[114:115], v[218:219], v[114:115] op_sel:[1,0]
	v_pk_mul_f32 v[118:119], v[218:219], v[118:119] op_sel:[1,0]
	v_pk_mul_f32 v[116:117], v[218:219], v[116:117] op_sel:[1,0]
	v_lshl_add_u64 v[142:143], s[0:1], 0, v[142:143]
	v_pk_mul_f32 v[144:145], v[218:219], v[146:147] op_sel:[1,0]
	v_pk_mul_f32 v[146:147], v[218:219], v[150:151] op_sel:[1,0]
	v_pk_mul_f32 v[126:127], v[218:219], v[126:127] op_sel:[1,0]
	v_pk_mul_f32 v[128:129], v[218:219], v[128:129] op_sel:[1,0]
	v_lshl_add_u64 v[142:143], v[142:143], 0, v[140:141]
	v_lshl_add_u64 v[44:45], s[0:1], 0, v[44:45]
	v_lshl_add_u64 v[44:45], v[44:45], 0, v[140:141]
	s_waitcnt vmcnt(0)
	v_pk_fma_f32 v[148:149], v[32:33], v[114:115], v[28:29]
	v_pk_fma_f32 v[114:115], v[30:31], v[122:123], v[26:27]
	v_pk_fma_f32 v[122:123], v[20:21], v[116:117], v[24:25]
	v_pk_fma_f32 v[116:117], v[18:19], v[118:119], v[22:23]
	v_pk_fma_f32 v[118:119], v[16:17], v[146:147], v[12:13]
	v_pk_fma_f32 v[144:145], v[14:15], v[144:145], v[10:11]
	v_pk_fma_f32 v[146:147], v[4:5], v[128:129], v[8:9]
	v_pk_fma_f32 v[128:129], v[2:3], v[126:127], v[6:7]
	v_cvt_pk_f16_f32 v114, v114, v115
	v_cvt_pk_f16_f32 v115, v148, v149
	v_cvt_pk_f16_f32 v116, v116, v117
	v_cvt_pk_f16_f32 v117, v122, v123
	v_cvt_pk_f16_f32 v126, v144, v145
	v_cvt_pk_f16_f32 v127, v118, v119
	v_cvt_pk_f16_f32 v128, v128, v129
	v_cvt_pk_f16_f32 v129, v146, v147
	flat_store_dwordx4 v[142:143], v[114:117] sc1
	flat_store_dwordx4 v[142:143], v[126:129] offset:256 sc1
	ds_read_b64 v[114:115], v35 offset:128
	v_lshl_add_u64 v[116:117], s[0:1], 0, v[120:121]
	v_lshl_add_u64 v[116:117], v[116:117], 0, v[140:141]
	s_waitcnt lgkmcnt(0)
	v_sub_f32_e32 v99, v98, v114
	v_sub_f32_e32 v98, v154, v114
	v_sub_f32_e32 v107, v106, v114
	v_sub_f32_e32 v106, v124, v114
	v_sub_f32_e32 v101, v100, v114
	v_sub_f32_e32 v100, v156, v114
	v_sub_f32_e32 v103, v102, v114
	v_sub_f32_e32 v102, v152, v114
	v_pk_mul_f32 v[106:107], v[114:115], v[106:107] op_sel:[1,0]
	v_pk_mul_f32 v[98:99], v[114:115], v[98:99] op_sel:[1,0]
	v_pk_mul_f32 v[102:103], v[114:115], v[102:103] op_sel:[1,0]
	v_pk_mul_f32 v[100:101], v[114:115], v[100:101] op_sel:[1,0]
	v_pk_fma_f32 v[122:123], v[32:33], v[98:99], v[28:29]
	v_pk_fma_f32 v[98:99], v[30:31], v[106:107], v[26:27]
	v_pk_fma_f32 v[106:107], v[20:21], v[100:101], v[24:25]
	v_pk_fma_f32 v[100:101], v[18:19], v[102:103], v[22:23]
	v_cvt_pk_f16_f32 v98, v98, v99
	v_cvt_pk_f16_f32 v99, v122, v123
	v_cvt_pk_f16_f32 v100, v100, v101
	v_cvt_pk_f16_f32 v101, v106, v107
	v_sub_f32_e32 v119, v157, v114
	v_sub_f32_e32 v118, v153, v114
	v_sub_f32_e32 v121, v155, v114
	v_sub_f32_e32 v120, v125, v114
	flat_store_dwordx4 v[116:117], v[98:101] sc1
	v_sub_f32_e32 v107, v111, v114
	v_sub_f32_e32 v106, v110, v114
	v_sub_f32_e32 v101, v113, v114
	v_sub_f32_e32 v100, v112, v114
	v_pk_mul_f32 v[120:121], v[114:115], v[120:121] op_sel:[1,0]
	v_pk_mul_f32 v[118:119], v[114:115], v[118:119] op_sel:[1,0]
	v_pk_mul_f32 v[106:107], v[114:115], v[106:107] op_sel:[1,0]
	v_pk_mul_f32 v[100:101], v[114:115], v[100:101] op_sel:[1,0]
	v_pk_fma_f32 v[102:103], v[16:17], v[118:119], v[12:13]
	v_pk_fma_f32 v[98:99], v[14:15], v[120:121], v[10:11]
	v_pk_fma_f32 v[110:111], v[4:5], v[100:101], v[8:9]
	v_pk_fma_f32 v[100:101], v[2:3], v[106:107], v[6:7]
	v_cvt_pk_f16_f32 v98, v98, v99
	v_cvt_pk_f16_f32 v99, v102, v103
	v_cvt_pk_f16_f32 v100, v100, v101
	v_cvt_pk_f16_f32 v101, v110, v111
	flat_store_dwordx4 v[116:117], v[98:101] offset:256 sc1
	ds_read_b64 v[98:99], v35 offset:256
	s_waitcnt lgkmcnt(0)
; __device__ __forceinline__ u32x4 pack8(f32x4 a, f32x4 b) { u32x4 w; w.x = cvtpk(a[0], a[1]); w.y = cvtpk(a[2], a[3]); w.z = cvtpk(b[0], b[1]); w.w = cvtpk(b[2], b[3]); return w; }
;     __device__ __forceinline__ void fused(AccT& acc, const Unit& u, int wr, int wc, int fr, int fq, LAS unsigned char* lx, int tid) const {
;     ...
;         f32x4 gv[2][2], bv[2][2];
; #pragma unroll
;         for (int bj = 0; bj < 2; ++bj)
; #pragma unroll
;             for (int n = 0; n < 2; ++n) { gv[bj][n] = *(const f32x4*)(g + EPI_COL(u, bj) + 4 * n); bv[bj][n] = *(const f32x4*)(b + EPI_COL(u, bj) + 4 * n); }
; #pragma unroll
;         for (int ai = 0; ai < 2; ++ai)
; #pragma unroll
;             for (int m = 0; m < 4; ++m) {
;                 const int row = EPI_ROW(u, ai, m); const f32x2 st = Sx[ai * 128 + wr * 64 + m * 16 + fr];
; #pragma unroll
;                 for (int bj = 0; bj < 2; ++bj) {
;                     const size_t off = (size_t)row * DM + EPI_COL(u, bj);
;                     const f32x4 y0 = (acc[ai][bj][m][0] - st.x) * st.y * gv[bj][0] + bv[bj][0], y1 = (acc[ai][bj][m][1] - st.x) * st.y * gv[bj][1] + bv[bj][1];
;                     if (F32OUT) { *(f32x4*)(o32 + off) = y0; *(f32x4*)(o32 + off + 4) = y1; }
;                     else *(u32x4*)(o16 + off) = pack8(y0, y1);
;                 }
	v_sub_f32_e32 v83, v82, v98
	v_sub_f32_e32 v82, v164, v98
	v_sub_f32_e32 v91, v90, v98
	v_sub_f32_e32 v90, v108, v98
	v_sub_f32_e32 v85, v84, v98
	v_sub_f32_e32 v84, v166, v98
	v_sub_f32_e32 v87, v86, v98
	v_sub_f32_e32 v86, v162, v98
	v_pk_mul_f32 v[90:91], v[98:99], v[90:91] op_sel:[1,0]
	v_pk_mul_f32 v[82:83], v[98:99], v[82:83] op_sel:[1,0]
	v_pk_mul_f32 v[86:87], v[98:99], v[86:87] op_sel:[1,0]
	v_pk_mul_f32 v[84:85], v[98:99], v[84:85] op_sel:[1,0]
	v_pk_fma_f32 v[100:101], v[32:33], v[82:83], v[28:29]
	v_pk_fma_f32 v[82:83], v[30:31], v[90:91], v[26:27]
	v_pk_fma_f32 v[90:91], v[20:21], v[84:85], v[24:25]
	v_pk_fma_f32 v[84:85], v[18:19], v[86:87], v[22:23]
	v_lshl_add_u64 v[86:87], s[0:1], 0, v[104:105]
	v_cvt_pk_f16_f32 v82, v82, v83
	v_cvt_pk_f16_f32 v83, v100, v101
	v_cvt_pk_f16_f32 v84, v84, v85
	v_cvt_pk_f16_f32 v85, v90, v91
	v_lshl_add_u64 v[86:87], v[86:87], 0, v[140:141]
	flat_store_dwordx4 v[86:87], v[82:85] sc1
	v_sub_f32_e32 v95, v95, v98
	v_sub_f32_e32 v94, v94, v98
	v_sub_f32_e32 v83, v167, v98
	v_sub_f32_e32 v82, v163, v98
	v_sub_f32_e32 v85, v165, v98
	v_sub_f32_e32 v84, v109, v98
	v_pk_mul_f32 v[84:85], v[98:99], v[84:85] op_sel:[1,0]
	v_pk_mul_f32 v[82:83], v[98:99], v[82:83] op_sel:[1,0]
	v_pk_mul_f32 v[94:95], v[98:99], v[94:95] op_sel:[1,0]
	v_pk_fma_f32 v[90:91], v[16:17], v[82:83], v[12:13]
	v_pk_fma_f32 v[82:83], v[14:15], v[84:85], v[10:11]
	v_sub_f32_e32 v85, v97, v98
	v_sub_f32_e32 v84, v96, v98
	v_pk_mul_f32 v[84:85], v[98:99], v[84:85] op_sel:[1,0]
	v_cvt_pk_f16_f32 v82, v82, v83
	v_pk_fma_f32 v[96:97], v[4:5], v[84:85], v[8:9]
	v_pk_fma_f32 v[84:85], v[2:3], v[94:95], v[6:7]
	v_cvt_pk_f16_f32 v83, v90, v91
	v_cvt_pk_f16_f32 v84, v84, v85
	v_cvt_pk_f16_f32 v85, v96, v97
	flat_store_dwordx4 v[86:87], v[82:85] offset:256 sc1
	ds_read_b64 v[82:83], v35 offset:384
	s_waitcnt lgkmcnt(0)
	v_sub_f32_e32 v67, v66, v82
	v_sub_f32_e32 v66, v170, v82
	v_sub_f32_e32 v75, v74, v82
	v_sub_f32_e32 v74, v92, v82
	v_sub_f32_e32 v69, v68, v82
	v_sub_f32_e32 v68, v172, v82
	v_sub_f32_e32 v71, v70, v82
	v_sub_f32_e32 v70, v168, v82
	v_pk_mul_f32 v[74:75], v[82:83], v[74:75] op_sel:[1,0]
	v_pk_mul_f32 v[66:67], v[82:83], v[66:67] op_sel:[1,0]
	v_pk_mul_f32 v[70:71], v[82:83], v[70:71] op_sel:[1,0]
	v_pk_mul_f32 v[68:69], v[82:83], v[68:69] op_sel:[1,0]
	v_pk_fma_f32 v[84:85], v[32:33], v[66:67], v[28:29]
	v_pk_fma_f32 v[66:67], v[30:31], v[74:75], v[26:27]
	v_pk_fma_f32 v[74:75], v[20:21], v[68:69], v[24:25]
	v_pk_fma_f32 v[68:69], v[18:19], v[70:71], v[22:23]
	v_lshl_add_u64 v[70:71], s[0:1], 0, v[88:89]
	v_cvt_pk_f16_f32 v66, v66, v67
	v_cvt_pk_f16_f32 v67, v84, v85
	v_cvt_pk_f16_f32 v68, v68, v69
	v_cvt_pk_f16_f32 v69, v74, v75
	v_lshl_add_u64 v[70:71], v[70:71], 0, v[140:141]
	flat_store_dwordx4 v[70:71], v[66:69] sc1
	v_sub_f32_e32 v79, v79, v82
	v_sub_f32_e32 v78, v78, v82
	v_sub_f32_e32 v67, v173, v82
	v_sub_f32_e32 v66, v169, v82
	v_sub_f32_e32 v69, v171, v82
	v_sub_f32_e32 v68, v93, v82
	v_pk_mul_f32 v[68:69], v[82:83], v[68:69] op_sel:[1,0]
	v_pk_mul_f32 v[66:67], v[82:83], v[66:67] op_sel:[1,0]
	v_pk_mul_f32 v[78:79], v[82:83], v[78:79] op_sel:[1,0]
	v_pk_fma_f32 v[74:75], v[16:17], v[66:67], v[12:13]
	v_pk_fma_f32 v[66:67], v[14:15], v[68:69], v[10:11]
	v_sub_f32_e32 v69, v81, v82
	v_sub_f32_e32 v68, v80, v82
	v_pk_mul_f32 v[68:69], v[82:83], v[68:69] op_sel:[1,0]
	v_cvt_pk_f16_f32 v66, v66, v67
	v_pk_fma_f32 v[80:81], v[4:5], v[68:69], v[8:9]
	v_pk_fma_f32 v[68:69], v[2:3], v[78:79], v[6:7]
	v_cvt_pk_f16_f32 v67, v74, v75
	v_cvt_pk_f16_f32 v68, v68, v69
	v_cvt_pk_f16_f32 v69, v80, v81
	flat_store_dwordx4 v[70:71], v[66:69] offset:256 sc1
	ds_read_b64 v[66:67], v35 offset:1024
	s_waitcnt lgkmcnt(0)
	v_sub_f32_e32 v51, v50, v66
	v_sub_f32_e32 v50, v176, v66
	v_sub_f32_e32 v59, v58, v66
	v_sub_f32_e32 v58, v76, v66
	v_sub_f32_e32 v53, v52, v66
	v_sub_f32_e32 v52, v178, v66
	v_sub_f32_e32 v55, v54, v66
	v_sub_f32_e32 v54, v174, v66
	v_pk_mul_f32 v[58:59], v[66:67], v[58:59] op_sel:[1,0]
	v_pk_mul_f32 v[50:51], v[66:67], v[50:51] op_sel:[1,0]
	v_pk_mul_f32 v[54:55], v[66:67], v[54:55] op_sel:[1,0]
	v_pk_mul_f32 v[52:53], v[66:67], v[52:53] op_sel:[1,0]
	v_pk_fma_f32 v[68:69], v[32:33], v[50:51], v[28:29]
	v_pk_fma_f32 v[50:51], v[30:31], v[58:59], v[26:27]
	v_pk_fma_f32 v[58:59], v[20:21], v[52:53], v[24:25]
	v_pk_fma_f32 v[52:53], v[18:19], v[54:55], v[22:23]
	v_lshl_add_u64 v[54:55], s[0:1], 0, v[72:73]
	v_cvt_pk_f16_f32 v50, v50, v51
	v_cvt_pk_f16_f32 v51, v68, v69
	v_cvt_pk_f16_f32 v52, v52, v53
	v_cvt_pk_f16_f32 v53, v58, v59
	v_lshl_add_u64 v[54:55], v[54:55], 0, v[140:141]
	flat_store_dwordx4 v[54:55], v[50:53] sc1
	v_sub_f32_e32 v63, v63, v66
	v_sub_f32_e32 v62, v62, v66
	v_sub_f32_e32 v51, v179, v66
	v_sub_f32_e32 v50, v175, v66
	v_sub_f32_e32 v53, v177, v66
	v_sub_f32_e32 v52, v77, v66
	v_pk_mul_f32 v[52:53], v[66:67], v[52:53] op_sel:[1,0]
	v_pk_mul_f32 v[50:51], v[66:67], v[50:51] op_sel:[1,0]
	v_pk_mul_f32 v[62:63], v[66:67], v[62:63] op_sel:[1,0]
	v_pk_fma_f32 v[58:59], v[16:17], v[50:51], v[12:13]
	v_pk_fma_f32 v[50:51], v[14:15], v[52:53], v[10:11]
	v_sub_f32_e32 v53, v65, v66
	v_sub_f32_e32 v52, v64, v66
	v_pk_mul_f32 v[52:53], v[66:67], v[52:53] op_sel:[1,0]
	v_cvt_pk_f16_f32 v50, v50, v51
	v_pk_fma_f32 v[64:65], v[4:5], v[52:53], v[8:9]
	v_pk_fma_f32 v[52:53], v[2:3], v[62:63], v[6:7]
	v_cvt_pk_f16_f32 v51, v58, v59
	v_cvt_pk_f16_f32 v52, v52, v53
	v_cvt_pk_f16_f32 v53, v64, v65
	flat_store_dwordx4 v[54:55], v[50:53] offset:256 sc1
	ds_read_b64 v[50:51], v35 offset:1152
	s_waitcnt lgkmcnt(0)
; __device__ __forceinline__ u32x4 pack8(f32x4 a, f32x4 b) { u32x4 w; w.x = cvtpk(a[0], a[1]); w.y = cvtpk(a[2], a[3]); w.z = cvtpk(b[0], b[1]); w.w = cvtpk(b[2], b[3]); return w; }
; __device__ __forceinline__ int otid() { int t = threadIdx.x; asm volatile("" : "+v"(t)); return t; }
; #define PG8_BAR __builtin_amdgcn_s_barrier()
; template <class Epi>
; __device__ __forceinline__ void gemm_phase(LAS unsigned char* lds, const Gemm g, const StaticOrder& S, const Epi& E) {
;     ...
;         if (wr == 0) PG8_BAR;
;         { const int t2 = otid(), w2 = t2 >> 6, l2 = t2 & 63;
;           if constexpr (Epi::FUSED_LN) E.fused(acc, cur, w2 >> 2, w2 & 3, l2 & 15, l2 >> 4, lds + STAGE_BYTES, t2);
;           else E(acc, cur, w2 >> 2, w2 & 3, l2 & 15, l2 >> 4); }
;         if (!has_next) break;
; #pragma unroll
;         for (int a = 0; a < 2; ++a)
; #pragma unroll
;             for (int b = 0; b < 2; ++b)
; #pragma unroll
;                 for (int m = 0; m < 4; ++m)
; #pragma unroll
;                     for (int n = 0; n < 2; ++n) acc[a][b][m][n] = (f32x4){0.f, 0.f, 0.f, 0.f};
;         cur = nxt; cA = nA; cB = nB; ++ui;
;         if (wr == 1) PG8_BAR;
;     __device__ __forceinline__ void fused(AccT& acc, const Unit& u, int wr, int wc, int fr, int fq, LAS unsigned char* lx, int tid) const {
;     ...
;         f32x4 gv[2][2], bv[2][2];
; #pragma unroll
;         for (int bj = 0; bj < 2; ++bj)
; #pragma unroll
;             for (int n = 0; n < 2; ++n) { gv[bj][n] = *(const f32x4*)(g + EPI_COL(u, bj) + 4 * n); bv[bj][n] = *(const f32x4*)(b + EPI_COL(u, bj) + 4 * n); }
; #pragma unroll
;         for (int ai = 0; ai < 2; ++ai)
; #pragma unroll
;             for (int m = 0; m < 4; ++m) {
;                 const int row = EPI_ROW(u, ai, m); const f32x2 st = Sx[ai * 128 + wr * 64 + m * 16 + fr];
; #pragma unroll
;                 for (int bj = 0; bj < 2; ++bj) {
;                     const size_t off = (size_t)row * DM + EPI_COL(u, bj);
;                     const f32x4 y0 = (acc[ai][bj][m][0] - st.x) * st.y * gv[bj][0] + bv[bj][0], y1 = (acc[ai][bj][m][1] - st.x) * st.y * gv[bj][1] + bv[bj][1];
;                     if (F32OUT) { *(f32x4*)(o32 + off) = y0; *(f32x4*)(o32 + off + 4) = y1; }
;                     else *(u32x4*)(o16 + off) = pack8(y0, y1);
;                 }
	v_sub_f32_e32 v43, v42, v50
	v_sub_f32_e32 v42, v60, v50
	v_sub_f32_e32 v53, v34, v50
	v_sub_f32_e32 v52, v182, v50
	v_pk_mul_f32 v[42:43], v[50:51], v[42:43] op_sel:[1,0]
	v_sub_f32_e32 v37, v36, v50
	v_sub_f32_e32 v36, v184, v50
	v_sub_f32_e32 v39, v38, v50
	v_sub_f32_e32 v38, v180, v50
	v_pk_mul_f32 v[52:53], v[50:51], v[52:53] op_sel:[1,0]
	v_pk_fma_f32 v[42:43], v[30:31], v[42:43], v[26:27]
	v_pk_mul_f32 v[38:39], v[50:51], v[38:39] op_sel:[1,0]
	v_pk_mul_f32 v[36:37], v[50:51], v[36:37] op_sel:[1,0]
	v_pk_fma_f32 v[52:53], v[32:33], v[52:53], v[28:29]
	v_pk_fma_f32 v[54:55], v[20:21], v[36:37], v[24:25]
	v_pk_fma_f32 v[38:39], v[18:19], v[38:39], v[22:23]
	v_cvt_pk_f16_f32 v36, v42, v43
	v_lshl_add_u64 v[42:43], s[0:1], 0, v[56:57]
	v_cvt_pk_f16_f32 v37, v52, v53
	v_cvt_pk_f16_f32 v38, v38, v39
	v_cvt_pk_f16_f32 v39, v54, v55
	v_lshl_add_u64 v[42:43], v[42:43], 0, v[140:141]
	flat_store_dwordx4 v[42:43], v[36:39] sc1
	v_sub_f32_e32 v47, v47, v50
	v_sub_f32_e32 v46, v46, v50
	v_sub_f32_e32 v37, v185, v50
	v_sub_f32_e32 v36, v181, v50
	v_sub_f32_e32 v39, v183, v50
	v_sub_f32_e32 v38, v61, v50
	v_pk_mul_f32 v[38:39], v[50:51], v[38:39] op_sel:[1,0]
	v_pk_mul_f32 v[36:37], v[50:51], v[36:37] op_sel:[1,0]
	v_pk_mul_f32 v[46:47], v[50:51], v[46:47] op_sel:[1,0]
	v_pk_fma_f32 v[52:53], v[16:17], v[36:37], v[12:13]
	v_pk_fma_f32 v[36:37], v[14:15], v[38:39], v[10:11]
	v_sub_f32_e32 v39, v49, v50
	v_sub_f32_e32 v38, v48, v50
	v_pk_mul_f32 v[38:39], v[50:51], v[38:39] op_sel:[1,0]
	v_cvt_pk_f16_f32 v36, v36, v37
	v_pk_fma_f32 v[48:49], v[4:5], v[38:39], v[8:9]
	v_pk_fma_f32 v[38:39], v[2:3], v[46:47], v[6:7]
	v_cvt_pk_f16_f32 v37, v52, v53
	v_cvt_pk_f16_f32 v38, v38, v39
	v_cvt_pk_f16_f32 v39, v48, v49
	flat_store_dwordx4 v[42:43], v[36:39] offset:256 sc1
	ds_read_b64 v[42:43], v35 offset:1280
	s_waitcnt lgkmcnt(0)
	v_sub_f32_e32 v49, v192, v42
	v_sub_f32_e32 v37, v200, v42
	v_sub_f32_e32 v36, v196, v42
	v_sub_f32_e32 v39, v194, v42
	v_sub_f32_e32 v38, v188, v42
	v_pk_mul_f32 v[38:39], v[42:43], v[38:39] op_sel:[1,0]
	v_pk_mul_f32 v[36:37], v[42:43], v[36:37] op_sel:[1,0]
	v_sub_f32_e32 v48, v190, v42
	v_pk_fma_f32 v[46:47], v[32:33], v[36:37], v[28:29]
	v_pk_fma_f32 v[36:37], v[30:31], v[38:39], v[26:27]
	v_sub_f32_e32 v39, v202, v42
	v_sub_f32_e32 v38, v198, v42
	v_pk_mul_f32 v[48:49], v[42:43], v[48:49] op_sel:[1,0]
	v_pk_mul_f32 v[38:39], v[42:43], v[38:39] op_sel:[1,0]
	v_cvt_pk_f16_f32 v36, v36, v37
	v_pk_fma_f32 v[50:51], v[20:21], v[38:39], v[24:25]
	v_pk_fma_f32 v[38:39], v[18:19], v[48:49], v[22:23]
	v_cvt_pk_f16_f32 v37, v46, v47
	v_cvt_pk_f16_f32 v38, v38, v39
	v_cvt_pk_f16_f32 v39, v50, v51
	flat_store_dwordx4 v[44:45], v[36:39] sc1
	v_sub_f32_e32 v41, v41, v42
	v_sub_f32_e32 v40, v40, v42
	v_sub_f32_e32 v37, v199, v42
	v_sub_f32_e32 v36, v191, v42
	v_sub_f32_e32 v39, v197, v42
	v_sub_f32_e32 v38, v189, v42
	v_pk_mul_f32 v[38:39], v[42:43], v[38:39] op_sel:[1,0]
	v_pk_mul_f32 v[36:37], v[42:43], v[36:37] op_sel:[1,0]
	v_pk_mul_f32 v[40:41], v[42:43], v[40:41] op_sel:[1,0]
	v_pk_fma_f32 v[46:47], v[16:17], v[36:37], v[12:13]
	v_pk_fma_f32 v[36:37], v[14:15], v[38:39], v[10:11]
	v_sub_f32_e32 v39, v187, v42
	v_sub_f32_e32 v38, v186, v42
	v_pk_mul_f32 v[38:39], v[42:43], v[38:39] op_sel:[1,0]
	v_cvt_pk_f16_f32 v36, v36, v37
	v_pk_fma_f32 v[42:43], v[4:5], v[38:39], v[8:9]
	v_pk_fma_f32 v[38:39], v[2:3], v[40:41], v[6:7]
	v_cvt_pk_f16_f32 v37, v46, v47
	v_cvt_pk_f16_f32 v38, v38, v39
	v_cvt_pk_f16_f32 v39, v42, v43
	flat_store_dwordx4 v[44:45], v[36:39] offset:256 sc1
	ds_read_b64 v[34:35], v35 offset:1408
	s_waitcnt lgkmcnt(0)
	v_sub_f32_e32 v37, v224, v34
	v_sub_f32_e32 v36, v214, v34
	v_sub_f32_e32 v39, v220, v34
	v_sub_f32_e32 v38, v208, v34
	v_pk_mul_f32 v[38:39], v[34:35], v[38:39] op_sel:[1,0]
	v_pk_mul_f32 v[36:37], v[34:35], v[36:37] op_sel:[1,0]
	v_pk_fma_f32 v[26:27], v[30:31], v[38:39], v[26:27]
	v_pk_fma_f32 v[28:29], v[32:33], v[36:37], v[28:29]
	v_sub_f32_e32 v31, v226, v34
	v_sub_f32_e32 v30, v222, v34
	v_sub_f32_e32 v33, v212, v34
	v_sub_f32_e32 v32, v210, v34
	v_pk_mul_f32 v[32:33], v[34:35], v[32:33] op_sel:[1,0]
	v_pk_mul_f32 v[30:31], v[34:35], v[30:31] op_sel:[1,0]
	s_nop 0
	v_pk_fma_f32 v[24:25], v[20:21], v[30:31], v[24:25]
	v_pk_fma_f32 v[20:21], v[18:19], v[32:33], v[22:23]
	v_lshl_add_u64 v[22:23], s[0:1], 0, v[204:205]
	v_cvt_pk_f16_f32 v18, v26, v27
	v_cvt_pk_f16_f32 v19, v28, v29
	v_cvt_pk_f16_f32 v20, v20, v21
	v_cvt_pk_f16_f32 v21, v24, v25
	v_lshl_add_u64 v[22:23], v[22:23], 0, v[140:141]
	flat_store_dwordx4 v[22:23], v[18:21] sc1
	s_mov_b64 s[0:1], -1
	s_nop 0
	v_sub_f32_e32 v19, v223, v34
	v_sub_f32_e32 v18, v211, v34
	v_sub_f32_e32 v21, v215, v34
	v_sub_f32_e32 v20, v209, v34
	v_pk_mul_f32 v[20:21], v[34:35], v[20:21] op_sel:[1,0]
	v_pk_mul_f32 v[18:19], v[34:35], v[18:19] op_sel:[1,0]
	v_pk_fma_f32 v[10:11], v[14:15], v[20:21], v[10:11]
	v_pk_fma_f32 v[12:13], v[16:17], v[18:19], v[12:13]
	v_sub_f32_e32 v15, v207, v34
	v_sub_f32_e32 v14, v206, v34
	v_sub_f32_e32 v17, v159, v34
	v_sub_f32_e32 v16, v158, v34
	v_pk_mul_f32 v[16:17], v[34:35], v[16:17] op_sel:[1,0]
	v_pk_mul_f32 v[14:15], v[34:35], v[14:15] op_sel:[1,0]
	s_nop 0
	v_pk_fma_f32 v[8:9], v[4:5], v[14:15], v[8:9]
	v_pk_fma_f32 v[4:5], v[2:3], v[16:17], v[6:7]
	v_cvt_pk_f16_f32 v2, v10, v11
	v_cvt_pk_f16_f32 v3, v12, v13
	v_cvt_pk_f16_f32 v4, v4, v5
	v_cvt_pk_f16_f32 v5, v8, v9
	flat_store_dwordx4 v[22:23], v[2:5] offset:256 sc1
	s_cbranch_vccnz .LBB0_64
	s_andn2_b64 vcc, exec, s[20:21]
	s_cbranch_vccnz .LBB0_63
	s_barrier
	s_branch .LBB0_63

; __device__ __forceinline__ u32x4 pack8(f32x4 a, f32x4 b) { u32x4 w; w.x = cvtpk(a[0], a[1]); w.y = cvtpk(a[2], a[3]); w.z = cvtpk(b[0], b[1]); w.w = cvtpk(b[2], b[3]); return w; }
; __device__ __forceinline__ float sigmoidf_(float x) { return __builtin_amdgcn_rcpf(1.0f + __expf(-x)); }
;     __device__ __forceinline__ void operator()(const AccT& acc, const Unit& u, int wr, int wc, int fr, int fq) const {
; #pragma unroll
;         for (int ai = 0; ai < 2; ++ai)
; #pragma unroll
;             for (int m = 0; m < 4; ++m) {
;                 const int row = EPI_ROW(u, ai, m);
;                 f32x4 h0, h1;
; #pragma unroll
;                 for (int e = 0; e < 4; ++e) { const float g0 = acc[ai][0][m][0][e], g1 = acc[ai][0][m][1][e];
;                     h0[e] = g0 * sigmoidf_(g0) * acc[ai][1][m][0][e]; h1[e] = g1 * sigmoidf_(g1) * acc[ai][1][m][1][e]; }
;                 *(u32x4*)(H + (size_t)row * DFF + u.pn * 128 + wc * 32 + 8 * fq) = pack8(h0, h1);
;             }
.LBB0_340:
	v_mov_b32_e32 v145, v216
	s_movk_i32 s11, 0x1600
	v_ashrrev_i32_e32 v0, 2, v145
	v_and_b32_e32 v0, 0xffffffc0, v0
	v_lshl_add_u32 v0, s40, 8, v0
	v_and_or_b32 v144, v145, 15, v0
	v_mul_f32_e32 v0, 0xbfb8aa3b, v126
	v_exp_f32_e32 v0, v0
	s_lshl_b32 s40, s2, 7
	v_readlane_b32 s2, v255, 4
	v_readlane_b32 s3, v255, 5
	v_add_f32_e32 v0, 1.0, v0
	v_rcp_f32_e32 v146, v0
	v_mul_f32_e32 v0, 0xbfb8aa3b, v118
	v_exp_f32_e32 v0, v0
	s_ashr_i32 s41, s40, 31
	s_lshl_b64 s[40:41], s[40:41], 1
	s_andn2_b64 vcc, exec, s[4:5]
	v_add_f32_e32 v0, 1.0, v0
	v_rcp_f32_e32 v148, v0
	v_mul_f32_e32 v0, 0xbfb8aa3b, v127
	v_exp_f32_e32 v0, v0
	s_nop 0
	v_add_f32_e32 v0, 1.0, v0
	v_rcp_f32_e32 v147, v0
	v_mul_f32_e32 v0, 0xbfb8aa3b, v119
	v_exp_f32_e32 v0, v0
	v_pk_mul_f32 v[126:127], v[126:127], v[146:147]
	s_nop 0
	v_pk_mul_f32 v[122:123], v[122:123], v[126:127]
	v_add_f32_e32 v0, 1.0, v0
	v_rcp_f32_e32 v149, v0
	v_mul_f32_e32 v0, 0xbfb8aa3b, v128
	v_exp_f32_e32 v0, v0
	v_pk_mul_f32 v[118:119], v[118:119], v[148:149]
	s_nop 0
	v_pk_mul_f32 v[114:115], v[114:115], v[118:119]
	v_add_f32_e32 v0, 1.0, v0
	v_rcp_f32_e32 v118, v0
	v_mul_f32_e32 v0, 0xbfb8aa3b, v120
	v_exp_f32_e32 v0, v0
	s_nop 0
	v_add_f32_e32 v0, 1.0, v0
	v_rcp_f32_e32 v126, v0
	v_mul_f32_e32 v0, 0xbfb8aa3b, v129
	v_exp_f32_e32 v0, v0
	s_nop 0
	v_add_f32_e32 v0, 1.0, v0
	v_rcp_f32_e32 v119, v0
	v_mul_f32_e32 v0, 0xbfb8aa3b, v121
	v_exp_f32_e32 v0, v0
	v_pk_mul_f32 v[118:119], v[128:129], v[118:119]
	s_nop 0
	v_pk_mul_f32 v[124:125], v[124:125], v[118:119]
	v_add_f32_e32 v0, 1.0, v0
	v_rcp_f32_e32 v127, v0
	v_and_b32_e32 v0, 0xc0, v145
	v_pk_mul_f32 v[118:119], v[120:121], v[126:127]
	s_nop 0
	v_pk_mul_f32 v[116:117], v[116:117], v[118:119]
	v_cvt_pk_f16_f32 v120, v114, v115
	v_mov_b64_e32 v[114:115], s[2:3]
	v_cvt_pk_f16_f32 v121, v116, v117
	v_mad_i64_i32 v[116:117], s[2:3], v144, s11, v[114:115]
	v_lshl_add_u64 v[116:117], v[116:117], 0, s[40:41]
	v_cvt_pk_f16_f32 v118, v122, v123
	v_lshl_add_u64 v[122:123], v[116:117], 0, v[0:1]
	v_and_b32_e32 v116, 48, v145
	v_mov_b32_e32 v117, v1
	v_cvt_pk_f16_f32 v119, v124, v125
	v_lshl_add_u64 v[122:123], v[122:123], 0, v[116:117]
	flat_store_dwordx4 v[122:123], v[118:121] sc1
	s_nop 1
	v_mul_f32_e32 v119, 0xbfb8aa3b, v102
	v_exp_f32_e32 v119, v119
	v_mul_f32_e32 v118, 0xbfb8aa3b, v110
	v_exp_f32_e32 v118, v118
	v_add_f32_e32 v119, 1.0, v119
	v_rcp_f32_e32 v120, v119
	v_mul_f32_e32 v119, 0xbfb8aa3b, v111
	v_exp_f32_e32 v119, v119
	v_add_f32_e32 v118, 1.0, v118
	v_rcp_f32_e32 v118, v118
	v_add_f32_e32 v119, 1.0, v119
	v_rcp_f32_e32 v119, v119
	s_nop 0
	v_pk_mul_f32 v[110:111], v[110:111], v[118:119]
	s_nop 0
	v_pk_mul_f32 v[106:107], v[106:107], v[110:111]
	v_mul_f32_e32 v110, 0xbfb8aa3b, v103
	v_exp_f32_e32 v110, v110
	s_nop 0
	v_add_f32_e32 v110, 1.0, v110
	v_rcp_f32_e32 v121, v110
	s_nop 0
	v_pk_mul_f32 v[102:103], v[102:103], v[120:121]
	s_nop 0
	v_pk_mul_f32 v[102:103], v[98:99], v[102:103]
	v_mul_f32_e32 v99, 0xbfb8aa3b, v104
	v_exp_f32_e32 v99, v99
	v_mul_f32_e32 v98, 0xbfb8aa3b, v112
	v_exp_f32_e32 v98, v98
	v_add_f32_e32 v99, 1.0, v99
	v_rcp_f32_e32 v110, v99
	v_mul_f32_e32 v99, 0xbfb8aa3b, v113
	v_exp_f32_e32 v99, v99
	v_add_f32_e32 v98, 1.0, v98
	v_rcp_f32_e32 v98, v98
	v_add_f32_e32 v99, 1.0, v99
	v_rcp_f32_e32 v99, v99
	s_nop 0
	v_pk_mul_f32 v[98:99], v[112:113], v[98:99]
	s_nop 0
	v_pk_mul_f32 v[108:109], v[108:109], v[98:99]
	v_mul_f32_e32 v98, 0xbfb8aa3b, v105
	v_exp_f32_e32 v98, v98
	s_nop 0
	v_add_f32_e32 v98, 1.0, v98
	v_rcp_f32_e32 v111, v98
	s_nop 0
	v_pk_mul_f32 v[98:99], v[104:105], v[110:111]
	v_or_b32_e32 v110, 16, v144
	v_pk_mul_f32 v[104:105], v[100:101], v[98:99]
	v_cvt_pk_f16_f32 v100, v102, v103
	v_mad_i64_i32 v[102:103], s[2:3], v110, s11, v[114:115]
	v_lshl_add_u64 v[102:103], v[102:103], 0, s[40:41]
	v_lshl_add_u64 v[102:103], v[102:103], 0, v[0:1]
	v_cvt_pk_f16_f32 v98, v106, v107
	v_cvt_pk_f16_f32 v99, v108, v109
	v_cvt_pk_f16_f32 v101, v104, v105
	v_lshl_add_u64 v[102:103], v[102:103], 0, v[116:117]
	flat_store_dwordx4 v[102:103], v[98:101] sc1
	s_nop 1
	v_mul_f32_e32 v99, 0xbfb8aa3b, v86
	v_exp_f32_e32 v99, v99
	v_mul_f32_e32 v98, 0xbfb8aa3b, v94
	v_exp_f32_e32 v98, v98
	v_add_f32_e32 v99, 1.0, v99
	v_rcp_f32_e32 v100, v99
	v_mul_f32_e32 v99, 0xbfb8aa3b, v95
	v_exp_f32_e32 v99, v99
	v_add_f32_e32 v98, 1.0, v98
	v_rcp_f32_e32 v98, v98
	v_add_f32_e32 v99, 1.0, v99
	v_rcp_f32_e32 v99, v99
	s_nop 0
	v_pk_mul_f32 v[94:95], v[94:95], v[98:99]
	s_nop 0
	v_pk_mul_f32 v[90:91], v[90:91], v[94:95]
	v_mul_f32_e32 v94, 0xbfb8aa3b, v87
	v_exp_f32_e32 v94, v94
	s_nop 0
	v_add_f32_e32 v94, 1.0, v94
	v_rcp_f32_e32 v101, v94
	s_nop 0
	v_pk_mul_f32 v[86:87], v[86:87], v[100:101]
	s_nop 0
	v_pk_mul_f32 v[86:87], v[82:83], v[86:87]
	v_mul_f32_e32 v83, 0xbfb8aa3b, v88
	v_exp_f32_e32 v83, v83
	v_mul_f32_e32 v82, 0xbfb8aa3b, v96
	v_exp_f32_e32 v82, v82
	v_add_f32_e32 v83, 1.0, v83
	v_rcp_f32_e32 v94, v83
	v_mul_f32_e32 v83, 0xbfb8aa3b, v97
	v_exp_f32_e32 v83, v83
	v_add_f32_e32 v82, 1.0, v82
	v_rcp_f32_e32 v82, v82
	v_add_f32_e32 v83, 1.0, v83
	v_rcp_f32_e32 v83, v83
	s_nop 0
	v_pk_mul_f32 v[82:83], v[96:97], v[82:83]
	s_nop 0
	v_pk_mul_f32 v[92:93], v[92:93], v[82:83]
	v_mul_f32_e32 v82, 0xbfb8aa3b, v89
	v_exp_f32_e32 v82, v82
	s_nop 0
	v_add_f32_e32 v82, 1.0, v82
	v_rcp_f32_e32 v95, v82
	s_nop 0
	v_pk_mul_f32 v[82:83], v[88:89], v[94:95]
	v_or_b32_e32 v94, 32, v144
	v_pk_mul_f32 v[88:89], v[84:85], v[82:83]
	v_cvt_pk_f16_f32 v84, v86, v87
	v_mad_i64_i32 v[86:87], s[2:3], v94, s11, v[114:115]
	v_lshl_add_u64 v[86:87], v[86:87], 0, s[40:41]
	v_lshl_add_u64 v[86:87], v[86:87], 0, v[0:1]
	v_cvt_pk_f16_f32 v82, v90, v91
; __device__ __forceinline__ u32x4 pack8(f32x4 a, f32x4 b) { u32x4 w; w.x = cvtpk(a[0], a[1]); w.y = cvtpk(a[2], a[3]); w.z = cvtpk(b[0], b[1]); w.w = cvtpk(b[2], b[3]); return w; }
; __device__ __forceinline__ float sigmoidf_(float x) { return __builtin_amdgcn_rcpf(1.0f + __expf(-x)); }
;     __device__ __forceinline__ void operator()(const AccT& acc, const Unit& u, int wr, int wc, int fr, int fq) const {
; #pragma unroll
;         for (int ai = 0; ai < 2; ++ai)
; #pragma unroll
;             for (int m = 0; m < 4; ++m) {
;                 const int row = EPI_ROW(u, ai, m);
;                 f32x4 h0, h1;
; #pragma unroll
;                 for (int e = 0; e < 4; ++e) { const float g0 = acc[ai][0][m][0][e], g1 = acc[ai][0][m][1][e];
;                     h0[e] = g0 * sigmoidf_(g0) * acc[ai][1][m][0][e]; h1[e] = g1 * sigmoidf_(g1) * acc[ai][1][m][1][e]; }
;                 *(u32x4*)(H + (size_t)row * DFF + u.pn * 128 + wc * 32 + 8 * fq) = pack8(h0, h1);
;             }
	v_cvt_pk_f16_f32 v83, v92, v93
	v_cvt_pk_f16_f32 v85, v88, v89
	v_lshl_add_u64 v[86:87], v[86:87], 0, v[116:117]
	flat_store_dwordx4 v[86:87], v[82:85] sc1
	s_nop 1
	v_mul_f32_e32 v83, 0xbfb8aa3b, v70
	v_exp_f32_e32 v83, v83
	v_mul_f32_e32 v82, 0xbfb8aa3b, v78
	v_exp_f32_e32 v82, v82
	v_add_f32_e32 v83, 1.0, v83
	v_rcp_f32_e32 v84, v83
	v_mul_f32_e32 v83, 0xbfb8aa3b, v79
	v_exp_f32_e32 v83, v83
	v_add_f32_e32 v82, 1.0, v82
	v_rcp_f32_e32 v82, v82
	v_add_f32_e32 v83, 1.0, v83
	v_rcp_f32_e32 v83, v83
	s_nop 0
	v_pk_mul_f32 v[78:79], v[78:79], v[82:83]
	s_nop 0
	v_pk_mul_f32 v[74:75], v[74:75], v[78:79]
	v_mul_f32_e32 v78, 0xbfb8aa3b, v71
	v_exp_f32_e32 v78, v78
	s_nop 0
	v_add_f32_e32 v78, 1.0, v78
	v_rcp_f32_e32 v85, v78
	s_nop 0
	v_pk_mul_f32 v[70:71], v[70:71], v[84:85]
	s_nop 0
	v_pk_mul_f32 v[70:71], v[66:67], v[70:71]
	v_mul_f32_e32 v67, 0xbfb8aa3b, v72
	v_exp_f32_e32 v67, v67
	v_mul_f32_e32 v66, 0xbfb8aa3b, v80
	v_exp_f32_e32 v66, v66
	v_add_f32_e32 v67, 1.0, v67
	v_rcp_f32_e32 v78, v67
	v_mul_f32_e32 v67, 0xbfb8aa3b, v81
	v_exp_f32_e32 v67, v67
	v_add_f32_e32 v66, 1.0, v66
	v_rcp_f32_e32 v66, v66
	v_add_f32_e32 v67, 1.0, v67
	v_rcp_f32_e32 v67, v67
	s_nop 0
	v_pk_mul_f32 v[66:67], v[80:81], v[66:67]
	s_nop 0
	v_pk_mul_f32 v[76:77], v[76:77], v[66:67]
	v_mul_f32_e32 v66, 0xbfb8aa3b, v73
	v_exp_f32_e32 v66, v66
	s_nop 0
	v_add_f32_e32 v66, 1.0, v66
	v_rcp_f32_e32 v79, v66
	s_nop 0
	v_pk_mul_f32 v[66:67], v[72:73], v[78:79]
	v_or_b32_e32 v78, 48, v144
	v_pk_mul_f32 v[72:73], v[68:69], v[66:67]
	v_cvt_pk_f16_f32 v68, v70, v71
	v_mad_i64_i32 v[70:71], s[2:3], v78, s11, v[114:115]
	v_lshl_add_u64 v[70:71], v[70:71], 0, s[40:41]
	v_lshl_add_u64 v[70:71], v[70:71], 0, v[0:1]
	v_cvt_pk_f16_f32 v66, v74, v75
	v_cvt_pk_f16_f32 v67, v76, v77
	v_cvt_pk_f16_f32 v69, v72, v73
	v_lshl_add_u64 v[70:71], v[70:71], 0, v[116:117]
	flat_store_dwordx4 v[70:71], v[66:69] sc1
	v_add_u32_e32 v70, 0x80, v144
	s_nop 0
	v_mul_f32_e32 v67, 0xbfb8aa3b, v54
	v_exp_f32_e32 v67, v67
	v_mul_f32_e32 v66, 0xbfb8aa3b, v62
	v_exp_f32_e32 v66, v66
	v_add_f32_e32 v67, 1.0, v67
	v_rcp_f32_e32 v68, v67
	v_mul_f32_e32 v67, 0xbfb8aa3b, v63
	v_exp_f32_e32 v67, v67
	v_add_f32_e32 v66, 1.0, v66
	v_rcp_f32_e32 v66, v66
	v_add_f32_e32 v67, 1.0, v67
	v_rcp_f32_e32 v67, v67
	s_nop 0
	v_pk_mul_f32 v[62:63], v[62:63], v[66:67]
	s_nop 0
	v_pk_mul_f32 v[58:59], v[58:59], v[62:63]
	v_mul_f32_e32 v62, 0xbfb8aa3b, v55
	v_exp_f32_e32 v62, v62
	s_nop 0
	v_add_f32_e32 v62, 1.0, v62
	v_rcp_f32_e32 v69, v62
	s_nop 0
	v_pk_mul_f32 v[54:55], v[54:55], v[68:69]
	s_nop 0
	v_pk_mul_f32 v[54:55], v[50:51], v[54:55]
	v_mul_f32_e32 v51, 0xbfb8aa3b, v56
	v_exp_f32_e32 v51, v51
	v_mul_f32_e32 v50, 0xbfb8aa3b, v64
	v_exp_f32_e32 v50, v50
	v_add_f32_e32 v51, 1.0, v51
	v_rcp_f32_e32 v62, v51
	v_mul_f32_e32 v51, 0xbfb8aa3b, v65
	v_exp_f32_e32 v51, v51
	v_add_f32_e32 v50, 1.0, v50
	v_rcp_f32_e32 v50, v50
	v_add_f32_e32 v51, 1.0, v51
	v_rcp_f32_e32 v51, v51
	s_nop 0
	v_pk_mul_f32 v[50:51], v[64:65], v[50:51]
	s_nop 0
	v_pk_mul_f32 v[60:61], v[60:61], v[50:51]
	v_mul_f32_e32 v50, 0xbfb8aa3b, v57
	v_exp_f32_e32 v50, v50
	s_nop 0
	v_add_f32_e32 v50, 1.0, v50
	v_rcp_f32_e32 v63, v50
	s_nop 0
	v_pk_mul_f32 v[50:51], v[56:57], v[62:63]
	s_nop 0
	v_pk_mul_f32 v[56:57], v[52:53], v[50:51]
	v_cvt_pk_f16_f32 v52, v54, v55
	v_mad_i64_i32 v[54:55], s[2:3], v70, s11, v[114:115]
	v_lshl_add_u64 v[54:55], v[54:55], 0, s[40:41]
	v_lshl_add_u64 v[54:55], v[54:55], 0, v[0:1]
	v_cvt_pk_f16_f32 v50, v58, v59
	v_cvt_pk_f16_f32 v51, v60, v61
	v_cvt_pk_f16_f32 v53, v56, v57
	v_lshl_add_u64 v[54:55], v[54:55], 0, v[116:117]
	flat_store_dwordx4 v[54:55], v[50:53] sc1
	s_nop 1
	v_mul_f32_e32 v51, 0xbfb8aa3b, v38
	v_exp_f32_e32 v51, v51
	v_mul_f32_e32 v50, 0xbfb8aa3b, v46
	v_exp_f32_e32 v50, v50
	v_add_f32_e32 v51, 1.0, v51
	v_rcp_f32_e32 v52, v51
	v_mul_f32_e32 v51, 0xbfb8aa3b, v47
	v_exp_f32_e32 v51, v51
	v_add_f32_e32 v50, 1.0, v50
	v_rcp_f32_e32 v50, v50
	v_add_f32_e32 v51, 1.0, v51
	v_rcp_f32_e32 v51, v51
	s_nop 0
	v_pk_mul_f32 v[46:47], v[46:47], v[50:51]
	s_nop 0
	v_pk_mul_f32 v[42:43], v[42:43], v[46:47]
	v_mul_f32_e32 v46, 0xbfb8aa3b, v39
	v_exp_f32_e32 v46, v46
	s_nop 0
	v_add_f32_e32 v46, 1.0, v46
	v_rcp_f32_e32 v53, v46
	s_nop 0
	v_pk_mul_f32 v[38:39], v[38:39], v[52:53]
	s_nop 0
	v_pk_mul_f32 v[38:39], v[34:35], v[38:39]
	v_mul_f32_e32 v35, 0xbfb8aa3b, v40
	v_exp_f32_e32 v35, v35
	v_mul_f32_e32 v34, 0xbfb8aa3b, v48
	v_exp_f32_e32 v34, v34
	v_add_f32_e32 v35, 1.0, v35
; __device__ __forceinline__ u32x4 pack8(f32x4 a, f32x4 b) { u32x4 w; w.x = cvtpk(a[0], a[1]); w.y = cvtpk(a[2], a[3]); w.z = cvtpk(b[0], b[1]); w.w = cvtpk(b[2], b[3]); return w; }
; __device__ __forceinline__ float sigmoidf_(float x) { return __builtin_amdgcn_rcpf(1.0f + __expf(-x)); }
;     __device__ __forceinline__ void operator()(const AccT& acc, const Unit& u, int wr, int wc, int fr, int fq) const {
; #pragma unroll
;         for (int ai = 0; ai < 2; ++ai)
; #pragma unroll
;             for (int m = 0; m < 4; ++m) {
;                 const int row = EPI_ROW(u, ai, m);
;                 f32x4 h0, h1;
; #pragma unroll
;                 for (int e = 0; e < 4; ++e) { const float g0 = acc[ai][0][m][0][e], g1 = acc[ai][0][m][1][e];
;                     h0[e] = g0 * sigmoidf_(g0) * acc[ai][1][m][0][e]; h1[e] = g1 * sigmoidf_(g1) * acc[ai][1][m][1][e]; }
;                 *(u32x4*)(H + (size_t)row * DFF + u.pn * 128 + wc * 32 + 8 * fq) = pack8(h0, h1);
;             }
	v_rcp_f32_e32 v46, v35
	v_mul_f32_e32 v35, 0xbfb8aa3b, v49
	v_exp_f32_e32 v35, v35
	v_add_f32_e32 v34, 1.0, v34
	v_rcp_f32_e32 v34, v34
	v_add_f32_e32 v35, 1.0, v35
	v_rcp_f32_e32 v35, v35
	s_nop 0
	v_pk_mul_f32 v[34:35], v[48:49], v[34:35]
	s_nop 0
	v_pk_mul_f32 v[44:45], v[44:45], v[34:35]
	v_mul_f32_e32 v34, 0xbfb8aa3b, v41
	v_exp_f32_e32 v34, v34
	s_nop 0
	v_add_f32_e32 v34, 1.0, v34
	v_rcp_f32_e32 v47, v34
	s_nop 0
	v_pk_mul_f32 v[34:35], v[40:41], v[46:47]
	v_add_u32_e32 v46, 0x90, v144
	v_pk_mul_f32 v[40:41], v[36:37], v[34:35]
	v_cvt_pk_f16_f32 v36, v38, v39
	v_mad_i64_i32 v[38:39], s[2:3], v46, s11, v[114:115]
	v_lshl_add_u64 v[38:39], v[38:39], 0, s[40:41]
	v_lshl_add_u64 v[38:39], v[38:39], 0, v[0:1]
	v_cvt_pk_f16_f32 v34, v42, v43
	v_cvt_pk_f16_f32 v35, v44, v45
	v_cvt_pk_f16_f32 v37, v40, v41
	v_lshl_add_u64 v[38:39], v[38:39], 0, v[116:117]
	flat_store_dwordx4 v[38:39], v[34:37] sc1
	s_nop 1
	v_mul_f32_e32 v35, 0xbfb8aa3b, v22
	v_exp_f32_e32 v35, v35
	v_mul_f32_e32 v34, 0xbfb8aa3b, v30
	v_exp_f32_e32 v34, v34
	v_add_f32_e32 v35, 1.0, v35
	v_rcp_f32_e32 v36, v35
	v_mul_f32_e32 v35, 0xbfb8aa3b, v31
	v_exp_f32_e32 v35, v35
	v_add_f32_e32 v34, 1.0, v34
	v_rcp_f32_e32 v34, v34
	v_add_f32_e32 v35, 1.0, v35
	v_rcp_f32_e32 v35, v35
	s_nop 0
	v_pk_mul_f32 v[30:31], v[30:31], v[34:35]
	s_nop 0
	v_pk_mul_f32 v[26:27], v[26:27], v[30:31]
	v_mul_f32_e32 v30, 0xbfb8aa3b, v23
	v_exp_f32_e32 v30, v30
	s_nop 0
	v_add_f32_e32 v30, 1.0, v30
	v_rcp_f32_e32 v37, v30
	s_nop 0
	v_pk_mul_f32 v[22:23], v[22:23], v[36:37]
	s_nop 0
	v_pk_mul_f32 v[22:23], v[18:19], v[22:23]
	v_mul_f32_e32 v19, 0xbfb8aa3b, v24
	v_exp_f32_e32 v19, v19
	v_mul_f32_e32 v18, 0xbfb8aa3b, v32
	v_exp_f32_e32 v18, v18
	v_add_f32_e32 v19, 1.0, v19
	v_rcp_f32_e32 v30, v19
	v_mul_f32_e32 v19, 0xbfb8aa3b, v33
	v_exp_f32_e32 v19, v19
	v_add_f32_e32 v18, 1.0, v18
	v_rcp_f32_e32 v18, v18
	v_add_f32_e32 v19, 1.0, v19
	v_rcp_f32_e32 v19, v19
	s_nop 0
	v_pk_mul_f32 v[18:19], v[32:33], v[18:19]
	s_nop 0
	v_pk_mul_f32 v[28:29], v[28:29], v[18:19]
	v_mul_f32_e32 v18, 0xbfb8aa3b, v25
	v_exp_f32_e32 v18, v18
	s_nop 0
	v_add_f32_e32 v18, 1.0, v18
	v_rcp_f32_e32 v31, v18
	s_nop 0
	v_pk_mul_f32 v[18:19], v[24:25], v[30:31]
	v_add_u32_e32 v30, 0xa0, v144
	v_pk_mul_f32 v[24:25], v[20:21], v[18:19]
	v_cvt_pk_f16_f32 v20, v22, v23
	v_mad_i64_i32 v[22:23], s[2:3], v30, s11, v[114:115]
	v_lshl_add_u64 v[22:23], v[22:23], 0, s[40:41]
	v_lshl_add_u64 v[22:23], v[22:23], 0, v[0:1]
	v_cvt_pk_f16_f32 v18, v26, v27
	v_cvt_pk_f16_f32 v19, v28, v29
	v_cvt_pk_f16_f32 v21, v24, v25
	v_lshl_add_u64 v[22:23], v[22:23], 0, v[116:117]
	flat_store_dwordx4 v[22:23], v[18:21] sc1
	s_nop 1
	v_mul_f32_e32 v19, 0xbfb8aa3b, v6
	v_exp_f32_e32 v19, v19
	v_mul_f32_e32 v18, 0xbfb8aa3b, v14
	v_exp_f32_e32 v18, v18
	v_add_f32_e32 v19, 1.0, v19
	v_rcp_f32_e32 v20, v19
	v_mul_f32_e32 v19, 0xbfb8aa3b, v15
	v_exp_f32_e32 v19, v19
	v_add_f32_e32 v18, 1.0, v18
	v_rcp_f32_e32 v18, v18
	v_add_f32_e32 v19, 1.0, v19
	v_rcp_f32_e32 v19, v19
	s_nop 0
	v_pk_mul_f32 v[14:15], v[14:15], v[18:19]
	s_nop 0
	v_pk_mul_f32 v[10:11], v[10:11], v[14:15]
	v_mul_f32_e32 v14, 0xbfb8aa3b, v7
	v_exp_f32_e32 v14, v14
	s_nop 0
	v_add_f32_e32 v14, 1.0, v14
	v_rcp_f32_e32 v21, v14
	s_nop 0
	v_pk_mul_f32 v[6:7], v[6:7], v[20:21]
	s_nop 0
	v_pk_mul_f32 v[6:7], v[2:3], v[6:7]
	v_mul_f32_e32 v3, 0xbfb8aa3b, v8
	v_exp_f32_e32 v3, v3
	v_mul_f32_e32 v2, 0xbfb8aa3b, v16
	v_exp_f32_e32 v2, v2
	v_add_f32_e32 v3, 1.0, v3
	v_rcp_f32_e32 v14, v3
	v_mul_f32_e32 v3, 0xbfb8aa3b, v17
	v_exp_f32_e32 v3, v3
	v_add_f32_e32 v2, 1.0, v2
	v_rcp_f32_e32 v2, v2
	v_add_f32_e32 v3, 1.0, v3
	v_rcp_f32_e32 v3, v3
	s_nop 0
	v_pk_mul_f32 v[2:3], v[16:17], v[2:3]
	s_nop 0
	v_pk_mul_f32 v[12:13], v[12:13], v[2:3]
	v_mul_f32_e32 v2, 0xbfb8aa3b, v9
	v_exp_f32_e32 v2, v2
	s_nop 0
	v_add_f32_e32 v2, 1.0, v2
	v_rcp_f32_e32 v15, v2
	s_nop 0
	v_pk_mul_f32 v[2:3], v[8:9], v[14:15]
	v_add_u32_e32 v14, 0xb0, v144
	v_pk_mul_f32 v[8:9], v[4:5], v[2:3]
	v_cvt_pk_f16_f32 v4, v6, v7
	v_mad_i64_i32 v[6:7], s[2:3], v14, s11, v[114:115]
	v_lshl_add_u64 v[6:7], v[6:7], 0, s[40:41]
	v_lshl_add_u64 v[6:7], v[6:7], 0, v[0:1]
	v_cvt_pk_f16_f32 v2, v10, v11
	v_cvt_pk_f16_f32 v3, v12, v13
	v_cvt_pk_f16_f32 v5, v8, v9
	v_lshl_add_u64 v[6:7], v[6:7], 0, v[116:117]
	s_mov_b64 s[40:41], -1
	flat_store_dwordx4 v[6:7], v[2:5] sc1
	s_cbranch_vccnz .LBB0_332
	s_andn2_b64 vcc, exec, s[0:1]
	s_cbranch_vccnz .LBB0_331
	s_barrier
	s_branch .LBB0_331

; __device__ __forceinline__ u32x4 pack8(f32x4 a, f32x4 b) { u32x4 w; w.x = cvtpk(a[0], a[1]); w.y = cvtpk(a[2], a[3]); w.z = cvtpk(b[0], b[1]); w.w = cvtpk(b[2], b[3]); return w; }
;     __device__ __forceinline__ void fused(AccT& acc, const Unit& u, int wr, int wc, int fr, int fq, LAS unsigned char* lx, int tid) const {
;     ...
;         f32x4 gv[2][2], bv[2][2];
; #pragma unroll
;         for (int bj = 0; bj < 2; ++bj)
; #pragma unroll
;             for (int n = 0; n < 2; ++n) { gv[bj][n] = *(const f32x4*)(g + EPI_COL(u, bj) + 4 * n); bv[bj][n] = *(const f32x4*)(b + EPI_COL(u, bj) + 4 * n); }
; #pragma unroll
;         for (int ai = 0; ai < 2; ++ai)
; #pragma unroll
;             for (int m = 0; m < 4; ++m) {
;                 const int row = EPI_ROW(u, ai, m); const f32x2 st = Sx[ai * 128 + wr * 64 + m * 16 + fr];
; #pragma unroll
;                 for (int bj = 0; bj < 2; ++bj) {
;                     const size_t off = (size_t)row * DM + EPI_COL(u, bj);
;                     const f32x4 y0 = (acc[ai][bj][m][0] - st.x) * st.y * gv[bj][0] + bv[bj][0], y1 = (acc[ai][bj][m][1] - st.x) * st.y * gv[bj][1] + bv[bj][1];
;                     if (F32OUT) { *(f32x4*)(o32 + off) = y0; *(f32x4*)(o32 + off + 4) = y1; }
;                     else *(u32x4*)(o16 + off) = pack8(y0, y1);
;                 }
.LBB0_414:
	s_or_b64 exec, exec, s[10:11]
	v_lshlrev_b64 v[2:3], 2, v[140:141]
	s_waitcnt lgkmcnt(0)
	s_barrier
	s_waitcnt lgkmcnt(0)
	v_lshl_add_u64 v[4:5], s[8:9], 0, v[2:3]
	v_lshl_add_u64 v[6:7], s[12:13], 0, v[2:3]
	flat_load_dwordx4 v[26:29], v[6:7]
	flat_load_dwordx4 v[30:33], v[4:5]
	flat_load_dwordx4 v[18:21], v[4:5] offset:16
	flat_load_dwordx4 v[22:25], v[6:7] offset:16
	flat_load_dwordx4 v[10:13], v[6:7] offset:512
	flat_load_dwordx4 v[14:17], v[4:5] offset:512
	s_nop 0
	flat_load_dwordx4 v[2:5], v[4:5] offset:528
	s_nop 0
	flat_load_dwordx4 v[6:9], v[6:7] offset:528
	v_lshlrev_b32_e32 v35, 3, v238
	s_add_i32 s0, 0, 0x22000
	v_lshlrev_b32_e32 v37, 3, v229
	v_add3_u32 v35, s0, v35, v37
	ds_read_b64 v[218:219], v35
	v_readlane_b32 s0, v255, 2
	v_readlane_b32 s1, v255, 3
	v_lshlrev_b64 v[140:141], 1, v[140:141]
	s_andn2_b64 vcc, exec, s[46:47]
	s_waitcnt lgkmcnt(0)
	v_sub_f32_e32 v115, v114, v218
	v_sub_f32_e32 v114, v148, v218
	v_sub_f32_e32 v123, v122, v218
	v_sub_f32_e32 v122, v144, v218
	v_sub_f32_e32 v117, v116, v218
	v_sub_f32_e32 v116, v150, v218
	v_sub_f32_e32 v119, v118, v218
	v_sub_f32_e32 v118, v146, v218
	v_sub_f32_e32 v151, v151, v218
	v_sub_f32_e32 v150, v147, v218
	v_sub_f32_e32 v147, v149, v218
	v_sub_f32_e32 v146, v145, v218
	v_sub_f32_e32 v129, v129, v218
	v_sub_f32_e32 v128, v128, v218
	v_sub_f32_e32 v127, v127, v218
	v_sub_f32_e32 v126, v126, v218
	v_pk_mul_f32 v[122:123], v[218:219], v[122:123] op_sel:[1,0]
	v_pk_mul_f32 v[114:115], v[218:219], v[114:115] op_sel:[1,0]
	v_pk_mul_f32 v[118:119], v[218:219], v[118:119] op_sel:[1,0]
	v_pk_mul_f32 v[116:117], v[218:219], v[116:117] op_sel:[1,0]
	v_lshl_add_u64 v[142:143], s[0:1], 0, v[142:143]
	v_pk_mul_f32 v[144:145], v[218:219], v[146:147] op_sel:[1,0]
	v_pk_mul_f32 v[146:147], v[218:219], v[150:151] op_sel:[1,0]
	v_pk_mul_f32 v[126:127], v[218:219], v[126:127] op_sel:[1,0]
	v_pk_mul_f32 v[128:129], v[218:219], v[128:129] op_sel:[1,0]
	v_lshl_add_u64 v[142:143], v[142:143], 0, v[140:141]
	v_lshl_add_u64 v[44:45], s[0:1], 0, v[44:45]
	v_lshl_add_u64 v[44:45], v[44:45], 0, v[140:141]
	s_waitcnt vmcnt(0)
	v_pk_fma_f32 v[148:149], v[32:33], v[114:115], v[28:29]
	v_pk_fma_f32 v[114:115], v[30:31], v[122:123], v[26:27]
	v_pk_fma_f32 v[122:123], v[20:21], v[116:117], v[24:25]
	v_pk_fma_f32 v[116:117], v[18:19], v[118:119], v[22:23]
	v_pk_fma_f32 v[118:119], v[16:17], v[146:147], v[12:13]
	v_pk_fma_f32 v[144:145], v[14:15], v[144:145], v[10:11]
	v_pk_fma_f32 v[146:147], v[4:5], v[128:129], v[8:9]
	v_pk_fma_f32 v[128:129], v[2:3], v[126:127], v[6:7]
	v_cvt_pk_f16_f32 v114, v114, v115
	v_cvt_pk_f16_f32 v115, v148, v149
	v_cvt_pk_f16_f32 v116, v116, v117
	v_cvt_pk_f16_f32 v117, v122, v123
	v_cvt_pk_f16_f32 v126, v144, v145
	v_cvt_pk_f16_f32 v127, v118, v119
	v_cvt_pk_f16_f32 v128, v128, v129
	v_cvt_pk_f16_f32 v129, v146, v147
	flat_store_dwordx4 v[142:143], v[114:117] sc1
	flat_store_dwordx4 v[142:143], v[126:129] offset:256 sc1
	ds_read_b64 v[114:115], v35 offset:128
	v_lshl_add_u64 v[116:117], s[0:1], 0, v[120:121]
	v_lshl_add_u64 v[116:117], v[116:117], 0, v[140:141]
	s_waitcnt lgkmcnt(0)
	v_sub_f32_e32 v99, v98, v114
	v_sub_f32_e32 v98, v154, v114
	v_sub_f32_e32 v107, v106, v114
	v_sub_f32_e32 v106, v124, v114
	v_sub_f32_e32 v101, v100, v114
	v_sub_f32_e32 v100, v156, v114
	v_sub_f32_e32 v103, v102, v114
	v_sub_f32_e32 v102, v152, v114
	v_pk_mul_f32 v[106:107], v[114:115], v[106:107] op_sel:[1,0]
	v_pk_mul_f32 v[98:99], v[114:115], v[98:99] op_sel:[1,0]
	v_pk_mul_f32 v[102:103], v[114:115], v[102:103] op_sel:[1,0]
	v_pk_mul_f32 v[100:101], v[114:115], v[100:101] op_sel:[1,0]
	v_pk_fma_f32 v[122:123], v[32:33], v[98:99], v[28:29]
	v_pk_fma_f32 v[98:99], v[30:31], v[106:107], v[26:27]
	v_pk_fma_f32 v[106:107], v[20:21], v[100:101], v[24:25]
	v_pk_fma_f32 v[100:101], v[18:19], v[102:103], v[22:23]
	v_cvt_pk_f16_f32 v98, v98, v99
	v_cvt_pk_f16_f32 v99, v122, v123
	v_cvt_pk_f16_f32 v100, v100, v101
	v_cvt_pk_f16_f32 v101, v106, v107
	v_sub_f32_e32 v119, v157, v114
	v_sub_f32_e32 v118, v153, v114
	v_sub_f32_e32 v121, v155, v114
	v_sub_f32_e32 v120, v125, v114
	flat_store_dwordx4 v[116:117], v[98:101] sc1
	v_sub_f32_e32 v107, v111, v114
	v_sub_f32_e32 v106, v110, v114
	v_sub_f32_e32 v101, v113, v114
	v_sub_f32_e32 v100, v112, v114
	v_pk_mul_f32 v[120:121], v[114:115], v[120:121] op_sel:[1,0]
	v_pk_mul_f32 v[118:119], v[114:115], v[118:119] op_sel:[1,0]
	v_pk_mul_f32 v[106:107], v[114:115], v[106:107] op_sel:[1,0]
	v_pk_mul_f32 v[100:101], v[114:115], v[100:101] op_sel:[1,0]
	v_pk_fma_f32 v[102:103], v[16:17], v[118:119], v[12:13]
	v_pk_fma_f32 v[98:99], v[14:15], v[120:121], v[10:11]
	v_pk_fma_f32 v[110:111], v[4:5], v[100:101], v[8:9]
	v_pk_fma_f32 v[100:101], v[2:3], v[106:107], v[6:7]
	v_cvt_pk_f16_f32 v98, v98, v99
	v_cvt_pk_f16_f32 v99, v102, v103
	v_cvt_pk_f16_f32 v100, v100, v101
	v_cvt_pk_f16_f32 v101, v110, v111
	flat_store_dwordx4 v[116:117], v[98:101] offset:256 sc1
	ds_read_b64 v[98:99], v35 offset:256
	s_waitcnt lgkmcnt(0)
; __device__ __forceinline__ u32x4 pack8(f32x4 a, f32x4 b) { u32x4 w; w.x = cvtpk(a[0], a[1]); w.y = cvtpk(a[2], a[3]); w.z = cvtpk(b[0], b[1]); w.w = cvtpk(b[2], b[3]); return w; }
;     __device__ __forceinline__ void fused(AccT& acc, const Unit& u, int wr, int wc, int fr, int fq, LAS unsigned char* lx, int tid) const {
;     ...
;         f32x4 gv[2][2], bv[2][2];
; #pragma unroll
;         for (int bj = 0; bj < 2; ++bj)
; #pragma unroll
;             for (int n = 0; n < 2; ++n) { gv[bj][n] = *(const f32x4*)(g + EPI_COL(u, bj) + 4 * n); bv[bj][n] = *(const f32x4*)(b + EPI_COL(u, bj) + 4 * n); }
; #pragma unroll
;         for (int ai = 0; ai < 2; ++ai)
; #pragma unroll
;             for (int m = 0; m < 4; ++m) {
;                 const int row = EPI_ROW(u, ai, m); const f32x2 st = Sx[ai * 128 + wr * 64 + m * 16 + fr];
; #pragma unroll
;                 for (int bj = 0; bj < 2; ++bj) {
;                     const size_t off = (size_t)row * DM + EPI_COL(u, bj);
;                     const f32x4 y0 = (acc[ai][bj][m][0] - st.x) * st.y * gv[bj][0] + bv[bj][0], y1 = (acc[ai][bj][m][1] - st.x) * st.y * gv[bj][1] + bv[bj][1];
;                     if (F32OUT) { *(f32x4*)(o32 + off) = y0; *(f32x4*)(o32 + off + 4) = y1; }
;                     else *(u32x4*)(o16 + off) = pack8(y0, y1);
;                 }
	v_sub_f32_e32 v83, v82, v98
	v_sub_f32_e32 v82, v164, v98
	v_sub_f32_e32 v91, v90, v98
	v_sub_f32_e32 v90, v108, v98
	v_sub_f32_e32 v85, v84, v98
	v_sub_f32_e32 v84, v166, v98
	v_sub_f32_e32 v87, v86, v98
	v_sub_f32_e32 v86, v162, v98
	v_pk_mul_f32 v[90:91], v[98:99], v[90:91] op_sel:[1,0]
	v_pk_mul_f32 v[82:83], v[98:99], v[82:83] op_sel:[1,0]
	v_pk_mul_f32 v[86:87], v[98:99], v[86:87] op_sel:[1,0]
	v_pk_mul_f32 v[84:85], v[98:99], v[84:85] op_sel:[1,0]
	v_pk_fma_f32 v[100:101], v[32:33], v[82:83], v[28:29]
	v_pk_fma_f32 v[82:83], v[30:31], v[90:91], v[26:27]
	v_pk_fma_f32 v[90:91], v[20:21], v[84:85], v[24:25]
	v_pk_fma_f32 v[84:85], v[18:19], v[86:87], v[22:23]
	v_lshl_add_u64 v[86:87], s[0:1], 0, v[104:105]
	v_cvt_pk_f16_f32 v82, v82, v83
	v_cvt_pk_f16_f32 v83, v100, v101
	v_cvt_pk_f16_f32 v84, v84, v85
	v_cvt_pk_f16_f32 v85, v90, v91
	v_lshl_add_u64 v[86:87], v[86:87], 0, v[140:141]
	flat_store_dwordx4 v[86:87], v[82:85] sc1
	v_sub_f32_e32 v95, v95, v98
	v_sub_f32_e32 v94, v94, v98
	v_sub_f32_e32 v83, v167, v98
	v_sub_f32_e32 v82, v163, v98
	v_sub_f32_e32 v85, v165, v98
	v_sub_f32_e32 v84, v109, v98
	v_pk_mul_f32 v[84:85], v[98:99], v[84:85] op_sel:[1,0]
	v_pk_mul_f32 v[82:83], v[98:99], v[82:83] op_sel:[1,0]
	v_pk_mul_f32 v[94:95], v[98:99], v[94:95] op_sel:[1,0]
	v_pk_fma_f32 v[90:91], v[16:17], v[82:83], v[12:13]
	v_pk_fma_f32 v[82:83], v[14:15], v[84:85], v[10:11]
	v_sub_f32_e32 v85, v97, v98
	v_sub_f32_e32 v84, v96, v98
	v_pk_mul_f32 v[84:85], v[98:99], v[84:85] op_sel:[1,0]
	v_cvt_pk_f16_f32 v82, v82, v83
	v_pk_fma_f32 v[96:97], v[4:5], v[84:85], v[8:9]
	v_pk_fma_f32 v[84:85], v[2:3], v[94:95], v[6:7]
	v_cvt_pk_f16_f32 v83, v90, v91
	v_cvt_pk_f16_f32 v84, v84, v85
	v_cvt_pk_f16_f32 v85, v96, v97
	flat_store_dwordx4 v[86:87], v[82:85] offset:256 sc1
	ds_read_b64 v[82:83], v35 offset:384
	s_waitcnt lgkmcnt(0)
	v_sub_f32_e32 v67, v66, v82
	v_sub_f32_e32 v66, v170, v82
	v_sub_f32_e32 v75, v74, v82
	v_sub_f32_e32 v74, v92, v82
	v_sub_f32_e32 v69, v68, v82
	v_sub_f32_e32 v68, v172, v82
	v_sub_f32_e32 v71, v70, v82
	v_sub_f32_e32 v70, v168, v82
	v_pk_mul_f32 v[74:75], v[82:83], v[74:75] op_sel:[1,0]
	v_pk_mul_f32 v[66:67], v[82:83], v[66:67] op_sel:[1,0]
	v_pk_mul_f32 v[70:71], v[82:83], v[70:71] op_sel:[1,0]
	v_pk_mul_f32 v[68:69], v[82:83], v[68:69] op_sel:[1,0]
	v_pk_fma_f32 v[84:85], v[32:33], v[66:67], v[28:29]
	v_pk_fma_f32 v[66:67], v[30:31], v[74:75], v[26:27]
	v_pk_fma_f32 v[74:75], v[20:21], v[68:69], v[24:25]
	v_pk_fma_f32 v[68:69], v[18:19], v[70:71], v[22:23]
	v_lshl_add_u64 v[70:71], s[0:1], 0, v[88:89]
	v_cvt_pk_f16_f32 v66, v66, v67
	v_cvt_pk_f16_f32 v67, v84, v85
	v_cvt_pk_f16_f32 v68, v68, v69
	v_cvt_pk_f16_f32 v69, v74, v75
	v_lshl_add_u64 v[70:71], v[70:71], 0, v[140:141]
	flat_store_dwordx4 v[70:71], v[66:69] sc1
	v_sub_f32_e32 v79, v79, v82
	v_sub_f32_e32 v78, v78, v82
	v_sub_f32_e32 v67, v173, v82
	v_sub_f32_e32 v66, v169, v82
	v_sub_f32_e32 v69, v171, v82
	v_sub_f32_e32 v68, v93, v82
	v_pk_mul_f32 v[68:69], v[82:83], v[68:69] op_sel:[1,0]
	v_pk_mul_f32 v[66:67], v[82:83], v[66:67] op_sel:[1,0]
	v_pk_mul_f32 v[78:79], v[82:83], v[78:79] op_sel:[1,0]
	v_pk_fma_f32 v[74:75], v[16:17], v[66:67], v[12:13]
	v_pk_fma_f32 v[66:67], v[14:15], v[68:69], v[10:11]
	v_sub_f32_e32 v69, v81, v82
	v_sub_f32_e32 v68, v80, v82
	v_pk_mul_f32 v[68:69], v[82:83], v[68:69] op_sel:[1,0]
	v_cvt_pk_f16_f32 v66, v66, v67
	v_pk_fma_f32 v[80:81], v[4:5], v[68:69], v[8:9]
	v_pk_fma_f32 v[68:69], v[2:3], v[78:79], v[6:7]
	v_cvt_pk_f16_f32 v67, v74, v75
	v_cvt_pk_f16_f32 v68, v68, v69
	v_cvt_pk_f16_f32 v69, v80, v81
	flat_store_dwordx4 v[70:71], v[66:69] offset:256 sc1
	ds_read_b64 v[66:67], v35 offset:1024
	s_waitcnt lgkmcnt(0)
	v_sub_f32_e32 v51, v50, v66
	v_sub_f32_e32 v50, v176, v66
	v_sub_f32_e32 v59, v58, v66
	v_sub_f32_e32 v58, v76, v66
	v_sub_f32_e32 v53, v52, v66
	v_sub_f32_e32 v52, v178, v66
	v_sub_f32_e32 v55, v54, v66
	v_sub_f32_e32 v54, v174, v66
	v_pk_mul_f32 v[58:59], v[66:67], v[58:59] op_sel:[1,0]
	v_pk_mul_f32 v[50:51], v[66:67], v[50:51] op_sel:[1,0]
	v_pk_mul_f32 v[54:55], v[66:67], v[54:55] op_sel:[1,0]
	v_pk_mul_f32 v[52:53], v[66:67], v[52:53] op_sel:[1,0]
	v_pk_fma_f32 v[68:69], v[32:33], v[50:51], v[28:29]
	v_pk_fma_f32 v[50:51], v[30:31], v[58:59], v[26:27]
	v_pk_fma_f32 v[58:59], v[20:21], v[52:53], v[24:25]
	v_pk_fma_f32 v[52:53], v[18:19], v[54:55], v[22:23]
	v_lshl_add_u64 v[54:55], s[0:1], 0, v[72:73]
	v_cvt_pk_f16_f32 v50, v50, v51
	v_cvt_pk_f16_f32 v51, v68, v69
	v_cvt_pk_f16_f32 v52, v52, v53
	v_cvt_pk_f16_f32 v53, v58, v59
	v_lshl_add_u64 v[54:55], v[54:55], 0, v[140:141]
	flat_store_dwordx4 v[54:55], v[50:53] sc1
	v_sub_f32_e32 v63, v63, v66
	v_sub_f32_e32 v62, v62, v66
	v_sub_f32_e32 v51, v179, v66
	v_sub_f32_e32 v50, v175, v66
	v_sub_f32_e32 v53, v177, v66
	v_sub_f32_e32 v52, v77, v66
	v_pk_mul_f32 v[52:53], v[66:67], v[52:53] op_sel:[1,0]
	v_pk_mul_f32 v[50:51], v[66:67], v[50:51] op_sel:[1,0]
	v_pk_mul_f32 v[62:63], v[66:67], v[62:63] op_sel:[1,0]
	v_pk_fma_f32 v[58:59], v[16:17], v[50:51], v[12:13]
	v_pk_fma_f32 v[50:51], v[14:15], v[52:53], v[10:11]
	v_sub_f32_e32 v53, v65, v66
	v_sub_f32_e32 v52, v64, v66
	v_pk_mul_f32 v[52:53], v[66:67], v[52:53] op_sel:[1,0]
	v_cvt_pk_f16_f32 v50, v50, v51
	v_pk_fma_f32 v[64:65], v[4:5], v[52:53], v[8:9]
	v_pk_fma_f32 v[52:53], v[2:3], v[62:63], v[6:7]
	v_cvt_pk_f16_f32 v51, v58, v59
	v_cvt_pk_f16_f32 v52, v52, v53
	v_cvt_pk_f16_f32 v53, v64, v65
	flat_store_dwordx4 v[54:55], v[50:53] offset:256 sc1
	ds_read_b64 v[50:51], v35 offset:1152
	s_waitcnt lgkmcnt(0)
; __device__ __forceinline__ u32x4 pack8(f32x4 a, f32x4 b) { u32x4 w; w.x = cvtpk(a[0], a[1]); w.y = cvtpk(a[2], a[3]); w.z = cvtpk(b[0], b[1]); w.w = cvtpk(b[2], b[3]); return w; }
; __device__ __forceinline__ int otid() { int t = threadIdx.x; asm volatile("" : "+v"(t)); return t; }
; #define PG8_BAR __builtin_amdgcn_s_barrier()
; template <class Epi>
; __device__ __forceinline__ void gemm_phase(LAS unsigned char* lds, const Gemm g, const StaticOrder& S, const Epi& E) {
;     ...
;         if (wr == 0) PG8_BAR;
;         { const int t2 = otid(), w2 = t2 >> 6, l2 = t2 & 63;
;           if constexpr (Epi::FUSED_LN) E.fused(acc, cur, w2 >> 2, w2 & 3, l2 & 15, l2 >> 4, lds + STAGE_BYTES, t2);
;           else E(acc, cur, w2 >> 2, w2 & 3, l2 & 15, l2 >> 4); }
;         if (!has_next) break;
; #pragma unroll
;         for (int a = 0; a < 2; ++a)
; #pragma unroll
;             for (int b = 0; b < 2; ++b)
; #pragma unroll
;                 for (int m = 0; m < 4; ++m)
; #pragma unroll
;                     for (int n = 0; n < 2; ++n) acc[a][b][m][n] = (f32x4){0.f, 0.f, 0.f, 0.f};
;         cur = nxt; cA = nA; cB = nB; ++ui;
;         if (wr == 1) PG8_BAR;
;     __device__ __forceinline__ void fused(AccT& acc, const Unit& u, int wr, int wc, int fr, int fq, LAS unsigned char* lx, int tid) const {
;     ...
;         f32x4 gv[2][2], bv[2][2];
; #pragma unroll
;         for (int bj = 0; bj < 2; ++bj)
; #pragma unroll
;             for (int n = 0; n < 2; ++n) { gv[bj][n] = *(const f32x4*)(g + EPI_COL(u, bj) + 4 * n); bv[bj][n] = *(const f32x4*)(b + EPI_COL(u, bj) + 4 * n); }
; #pragma unroll
;         for (int ai = 0; ai < 2; ++ai)
; #pragma unroll
;             for (int m = 0; m < 4; ++m) {
;                 const int row = EPI_ROW(u, ai, m); const f32x2 st = Sx[ai * 128 + wr * 64 + m * 16 + fr];
; #pragma unroll
;                 for (int bj = 0; bj < 2; ++bj) {
;                     const size_t off = (size_t)row * DM + EPI_COL(u, bj);
;                     const f32x4 y0 = (acc[ai][bj][m][0] - st.x) * st.y * gv[bj][0] + bv[bj][0], y1 = (acc[ai][bj][m][1] - st.x) * st.y * gv[bj][1] + bv[bj][1];
;                     if (F32OUT) { *(f32x4*)(o32 + off) = y0; *(f32x4*)(o32 + off + 4) = y1; }
;                     else *(u32x4*)(o16 + off) = pack8(y0, y1);
;                 }
	v_sub_f32_e32 v43, v42, v50
	v_sub_f32_e32 v42, v60, v50
	v_sub_f32_e32 v53, v34, v50
	v_sub_f32_e32 v52, v182, v50
	v_pk_mul_f32 v[42:43], v[50:51], v[42:43] op_sel:[1,0]
	v_sub_f32_e32 v37, v36, v50
	v_sub_f32_e32 v36, v184, v50
	v_sub_f32_e32 v39, v38, v50
	v_sub_f32_e32 v38, v180, v50
	v_pk_mul_f32 v[52:53], v[50:51], v[52:53] op_sel:[1,0]
	v_pk_fma_f32 v[42:43], v[30:31], v[42:43], v[26:27]
	v_pk_mul_f32 v[38:39], v[50:51], v[38:39] op_sel:[1,0]
	v_pk_mul_f32 v[36:37], v[50:51], v[36:37] op_sel:[1,0]
	v_pk_fma_f32 v[52:53], v[32:33], v[52:53], v[28:29]
	v_pk_fma_f32 v[54:55], v[20:21], v[36:37], v[24:25]
	v_pk_fma_f32 v[38:39], v[18:19], v[38:39], v[22:23]
	v_cvt_pk_f16_f32 v36, v42, v43
	v_lshl_add_u64 v[42:43], s[0:1], 0, v[56:57]
	v_cvt_pk_f16_f32 v37, v52, v53
	v_cvt_pk_f16_f32 v38, v38, v39
	v_cvt_pk_f16_f32 v39, v54, v55
	v_lshl_add_u64 v[42:43], v[42:43], 0, v[140:141]
	flat_store_dwordx4 v[42:43], v[36:39] sc1
	v_sub_f32_e32 v47, v47, v50
	v_sub_f32_e32 v46, v46, v50
	v_sub_f32_e32 v37, v185, v50
	v_sub_f32_e32 v36, v181, v50
	v_sub_f32_e32 v39, v183, v50
	v_sub_f32_e32 v38, v61, v50
	v_pk_mul_f32 v[38:39], v[50:51], v[38:39] op_sel:[1,0]
	v_pk_mul_f32 v[36:37], v[50:51], v[36:37] op_sel:[1,0]
	v_pk_mul_f32 v[46:47], v[50:51], v[46:47] op_sel:[1,0]
	v_pk_fma_f32 v[52:53], v[16:17], v[36:37], v[12:13]
	v_pk_fma_f32 v[36:37], v[14:15], v[38:39], v[10:11]
	v_sub_f32_e32 v39, v49, v50
	v_sub_f32_e32 v38, v48, v50
	v_pk_mul_f32 v[38:39], v[50:51], v[38:39] op_sel:[1,0]
	v_cvt_pk_f16_f32 v36, v36, v37
	v_pk_fma_f32 v[48:49], v[4:5], v[38:39], v[8:9]
	v_pk_fma_f32 v[38:39], v[2:3], v[46:47], v[6:7]
	v_cvt_pk_f16_f32 v37, v52, v53
	v_cvt_pk_f16_f32 v38, v38, v39
	v_cvt_pk_f16_f32 v39, v48, v49
	flat_store_dwordx4 v[42:43], v[36:39] offset:256 sc1
	ds_read_b64 v[42:43], v35 offset:1280
	s_waitcnt lgkmcnt(0)
	v_sub_f32_e32 v49, v192, v42
	v_sub_f32_e32 v37, v200, v42
	v_sub_f32_e32 v36, v196, v42
	v_sub_f32_e32 v39, v194, v42
	v_sub_f32_e32 v38, v188, v42
	v_pk_mul_f32 v[38:39], v[42:43], v[38:39] op_sel:[1,0]
	v_pk_mul_f32 v[36:37], v[42:43], v[36:37] op_sel:[1,0]
	v_sub_f32_e32 v48, v190, v42
	v_pk_fma_f32 v[46:47], v[32:33], v[36:37], v[28:29]
	v_pk_fma_f32 v[36:37], v[30:31], v[38:39], v[26:27]
	v_sub_f32_e32 v39, v202, v42
	v_sub_f32_e32 v38, v198, v42
	v_pk_mul_f32 v[48:49], v[42:43], v[48:49] op_sel:[1,0]
	v_pk_mul_f32 v[38:39], v[42:43], v[38:39] op_sel:[1,0]
	v_cvt_pk_f16_f32 v36, v36, v37
	v_pk_fma_f32 v[50:51], v[20:21], v[38:39], v[24:25]
	v_pk_fma_f32 v[38:39], v[18:19], v[48:49], v[22:23]
	v_cvt_pk_f16_f32 v37, v46, v47
	v_cvt_pk_f16_f32 v38, v38, v39
	v_cvt_pk_f16_f32 v39, v50, v51
	flat_store_dwordx4 v[44:45], v[36:39] sc1
	v_sub_f32_e32 v41, v41, v42
	v_sub_f32_e32 v40, v40, v42
	v_sub_f32_e32 v37, v199, v42
	v_sub_f32_e32 v36, v191, v42
	v_sub_f32_e32 v39, v197, v42
	v_sub_f32_e32 v38, v189, v42
	v_pk_mul_f32 v[38:39], v[42:43], v[38:39] op_sel:[1,0]
	v_pk_mul_f32 v[36:37], v[42:43], v[36:37] op_sel:[1,0]
	v_pk_mul_f32 v[40:41], v[42:43], v[40:41] op_sel:[1,0]
	v_pk_fma_f32 v[46:47], v[16:17], v[36:37], v[12:13]
	v_pk_fma_f32 v[36:37], v[14:15], v[38:39], v[10:11]
	v_sub_f32_e32 v39, v187, v42
	v_sub_f32_e32 v38, v186, v42
	v_pk_mul_f32 v[38:39], v[42:43], v[38:39] op_sel:[1,0]
	v_cvt_pk_f16_f32 v36, v36, v37
	v_pk_fma_f32 v[42:43], v[4:5], v[38:39], v[8:9]
	v_pk_fma_f32 v[38:39], v[2:3], v[40:41], v[6:7]
	v_cvt_pk_f16_f32 v37, v46, v47
	v_cvt_pk_f16_f32 v38, v38, v39
	v_cvt_pk_f16_f32 v39, v42, v43
	flat_store_dwordx4 v[44:45], v[36:39] offset:256 sc1
	ds_read_b64 v[34:35], v35 offset:1408
	s_waitcnt lgkmcnt(0)
	v_sub_f32_e32 v37, v224, v34
	v_sub_f32_e32 v36, v214, v34
	v_sub_f32_e32 v39, v220, v34
	v_sub_f32_e32 v38, v208, v34
	v_pk_mul_f32 v[38:39], v[34:35], v[38:39] op_sel:[1,0]
	v_pk_mul_f32 v[36:37], v[34:35], v[36:37] op_sel:[1,0]
	v_pk_fma_f32 v[26:27], v[30:31], v[38:39], v[26:27]
	v_pk_fma_f32 v[28:29], v[32:33], v[36:37], v[28:29]
	v_sub_f32_e32 v31, v226, v34
	v_sub_f32_e32 v30, v222, v34
	v_sub_f32_e32 v33, v212, v34
	v_sub_f32_e32 v32, v210, v34
	v_pk_mul_f32 v[32:33], v[34:35], v[32:33] op_sel:[1,0]
	v_pk_mul_f32 v[30:31], v[34:35], v[30:31] op_sel:[1,0]
	s_nop 0
	v_pk_fma_f32 v[24:25], v[20:21], v[30:31], v[24:25]
	v_pk_fma_f32 v[20:21], v[18:19], v[32:33], v[22:23]
	v_lshl_add_u64 v[22:23], s[0:1], 0, v[204:205]
	v_cvt_pk_f16_f32 v18, v26, v27
	v_cvt_pk_f16_f32 v19, v28, v29
	v_cvt_pk_f16_f32 v20, v20, v21
	v_cvt_pk_f16_f32 v21, v24, v25
	v_lshl_add_u64 v[22:23], v[22:23], 0, v[140:141]
	flat_store_dwordx4 v[22:23], v[18:21] sc1
	s_mov_b64 s[0:1], -1
	s_nop 0
	v_sub_f32_e32 v19, v223, v34
	v_sub_f32_e32 v18, v211, v34
	v_sub_f32_e32 v21, v215, v34
	v_sub_f32_e32 v20, v209, v34
	v_pk_mul_f32 v[20:21], v[34:35], v[20:21] op_sel:[1,0]
	v_pk_mul_f32 v[18:19], v[34:35], v[18:19] op_sel:[1,0]
	v_pk_fma_f32 v[10:11], v[14:15], v[20:21], v[10:11]
	v_pk_fma_f32 v[12:13], v[16:17], v[18:19], v[12:13]
	v_sub_f32_e32 v15, v207, v34
	v_sub_f32_e32 v14, v206, v34
	v_sub_f32_e32 v17, v159, v34
	v_sub_f32_e32 v16, v158, v34
	v_pk_mul_f32 v[16:17], v[34:35], v[16:17] op_sel:[1,0]
	v_pk_mul_f32 v[14:15], v[34:35], v[14:15] op_sel:[1,0]
	s_nop 0
	v_pk_fma_f32 v[8:9], v[4:5], v[14:15], v[8:9]
	v_pk_fma_f32 v[4:5], v[2:3], v[16:17], v[6:7]
	v_cvt_pk_f16_f32 v2, v10, v11
	v_cvt_pk_f16_f32 v3, v12, v13
	v_cvt_pk_f16_f32 v4, v4, v5
	v_cvt_pk_f16_f32 v5, v8, v9
	flat_store_dwordx4 v[22:23], v[2:5] offset:256 sc1
	s_cbranch_vccnz .LBB0_364
	s_andn2_b64 vcc, exec, s[6:7]
	s_cbranch_vccnz .LBB0_363
	s_barrier
	s_branch .LBB0_363

; __device__ __forceinline__ u32x4 pack8(f32x4 a, f32x4 b) { u32x4 w; w.x = cvtpk(a[0], a[1]); w.y = cvtpk(a[2], a[3]); w.z = cvtpk(b[0], b[1]); w.w = cvtpk(b[2], b[3]); return w; }
; __device__ __forceinline__ float sumsq4(f32x4 x) { return (x[0] * x[0] + x[1] * x[1]) + (x[2] * x[2] + x[3] * x[3]); }
;     __device__ __forceinline__ void operator()(const AccT& acc, const Unit& u, int wr, int wc, int fr, int fq) const {
; #pragma unroll
;         for (int ai = 0; ai < 2; ++ai)
; #pragma unroll
;             for (int m = 0; m < 4; ++m) {
;                 const int row = EPI_ROW(u, ai, m);
; #pragma unroll
;                 for (int bj = 0; bj < 2; ++bj) *(u32x4*)(U + (size_t)row * LDU + EPI_COL(u, bj)) = pack8(acc[ai][bj][m][0], acc[ai][bj][m][1]);
;             }
;         if (u.pn >= 3) {
;             float* sp = u.pn == 3 ? ssq_q : ssq_kv; const float w1 = u.pn == 3 ? 1.f : 0.f;
; #pragma unroll
;             for (int ai = 0; ai < 2; ++ai)
; #pragma unroll
;                 for (int m = 0; m < 4; ++m) {
;                     float s = (sumsq4(acc[ai][0][m][0]) + sumsq4(acc[ai][0][m][1])) + w1 * (sumsq4(acc[ai][1][m][0]) + sumsq4(acc[ai][1][m][1]));
;                     s += __shfl_xor(s, 16); s += __shfl_xor(s, 32);
;                     if (fq == 0) unsafeAtomicAdd(sp + EPI_ROW(u, ai, m), s);
;                 }
.LBB0_885:
	v_mov_b32_e32 v141, v216
	s_lshl_b32 s2, s18, 8
	v_ashrrev_i32_e32 v140, 2, v141
	v_and_b32_e32 v140, 0xffffffc0, v140
	v_lshl_add_u32 v140, s20, 8, v140
	v_bfe_u32 v146, v141, 4, 2
	v_and_or_b32 v140, v141, 15, v140
	v_lshrrev_b32_e32 v141, 1, v141
	v_and_b32_e32 v141, 0x60, v141
	v_lshlrev_b32_e32 v144, 3, v146
	v_or3_b32 v144, v141, s2, v144
	v_readlane_b32 s2, v255, 2
	v_readlane_b32 s3, v255, 3
	v_ashrrev_i32_e32 v145, 31, v144
	v_lshlrev_b64 v[144:145], 1, v[144:145]
	v_mov_b64_e32 v[152:153], s[2:3]
	v_mad_i64_i32 v[154:155], s[2:3], v140, s61, v[152:153]
	v_cvt_pk_f16_f32 v148, v126, v127
	v_cvt_pk_f16_f32 v149, v128, v129
	v_cvt_pk_f16_f32 v150, v122, v123
	v_cvt_pk_f16_f32 v151, v124, v125
	v_lshl_add_u64 v[154:155], v[154:155], 0, v[144:145]
	flat_store_dwordx4 v[154:155], v[148:151] sc1
	v_or_b32_e32 v141, 16, v140
	s_cmp_lt_i32 s18, 3
	v_cvt_pk_f16_f32 v148, v118, v119
	v_cvt_pk_f16_f32 v149, v120, v121
	v_cvt_pk_f16_f32 v150, v114, v115
	v_cvt_pk_f16_f32 v151, v116, v117
	flat_store_dwordx4 v[154:155], v[148:151] offset:256 sc1
	v_mad_i64_i32 v[154:155], s[2:3], v141, s61, v[152:153]
	s_nop 0
	v_cvt_pk_f16_f32 v148, v110, v111
	v_cvt_pk_f16_f32 v149, v112, v113
	v_cvt_pk_f16_f32 v150, v106, v107
	v_cvt_pk_f16_f32 v151, v108, v109
	v_lshl_add_u64 v[154:155], v[154:155], 0, v[144:145]
	flat_store_dwordx4 v[154:155], v[148:151] sc1
	v_or_b32_e32 v141, 32, v140
	s_nop 0
	v_cvt_pk_f16_f32 v148, v102, v103
	v_cvt_pk_f16_f32 v149, v104, v105
	v_cvt_pk_f16_f32 v150, v98, v99
	v_cvt_pk_f16_f32 v151, v100, v101
	flat_store_dwordx4 v[154:155], v[148:151] offset:256 sc1
	v_mad_i64_i32 v[154:155], s[2:3], v141, s61, v[152:153]
	s_nop 0
	v_cvt_pk_f16_f32 v148, v94, v95
	v_cvt_pk_f16_f32 v149, v96, v97
	v_cvt_pk_f16_f32 v150, v90, v91
	v_cvt_pk_f16_f32 v151, v92, v93
	v_lshl_add_u64 v[154:155], v[154:155], 0, v[144:145]
	flat_store_dwordx4 v[154:155], v[148:151] sc1
	v_or_b32_e32 v141, 48, v140
	s_nop 0
	v_cvt_pk_f16_f32 v148, v86, v87
	v_cvt_pk_f16_f32 v149, v88, v89
	v_cvt_pk_f16_f32 v150, v82, v83
	v_cvt_pk_f16_f32 v151, v84, v85
	flat_store_dwordx4 v[154:155], v[148:151] offset:256 sc1
	v_mad_i64_i32 v[154:155], s[2:3], v141, s61, v[152:153]
	s_nop 0
	v_cvt_pk_f16_f32 v148, v78, v79
	v_cvt_pk_f16_f32 v149, v80, v81
	v_cvt_pk_f16_f32 v150, v74, v75
	v_cvt_pk_f16_f32 v151, v76, v77
	v_lshl_add_u64 v[154:155], v[154:155], 0, v[144:145]
	flat_store_dwordx4 v[154:155], v[148:151] sc1
	v_add_u32_e32 v141, 0x80, v140
	s_nop 0
	v_cvt_pk_f16_f32 v148, v70, v71
	v_cvt_pk_f16_f32 v149, v72, v73
	v_cvt_pk_f16_f32 v150, v66, v67
	v_cvt_pk_f16_f32 v151, v68, v69
	flat_store_dwordx4 v[154:155], v[148:151] offset:256 sc1
	v_mad_i64_i32 v[154:155], s[2:3], v141, s61, v[152:153]
	s_nop 0
	v_cvt_pk_f16_f32 v148, v62, v63
	v_cvt_pk_f16_f32 v149, v64, v65
	v_cvt_pk_f16_f32 v150, v58, v59
	v_cvt_pk_f16_f32 v151, v60, v61
	v_lshl_add_u64 v[154:155], v[154:155], 0, v[144:145]
	flat_store_dwordx4 v[154:155], v[148:151] sc1
	v_add_u32_e32 v141, 0x90, v140
	s_nop 0
	v_cvt_pk_f16_f32 v148, v54, v55
	v_cvt_pk_f16_f32 v149, v56, v57
	v_cvt_pk_f16_f32 v150, v50, v51
	v_cvt_pk_f16_f32 v151, v52, v53
	flat_store_dwordx4 v[154:155], v[148:151] offset:256 sc1
	v_mad_i64_i32 v[154:155], s[2:3], v141, s61, v[152:153]
	s_nop 0
	v_cvt_pk_f16_f32 v148, v46, v47
	v_cvt_pk_f16_f32 v149, v48, v49
	v_cvt_pk_f16_f32 v150, v42, v43
	v_cvt_pk_f16_f32 v151, v44, v45
	v_lshl_add_u64 v[154:155], v[154:155], 0, v[144:145]
	flat_store_dwordx4 v[154:155], v[148:151] sc1
	v_add_u32_e32 v141, 0xa0, v140
	s_nop 0
	v_cvt_pk_f16_f32 v148, v38, v39
	v_cvt_pk_f16_f32 v149, v40, v41
	v_cvt_pk_f16_f32 v150, v34, v35
	v_cvt_pk_f16_f32 v151, v36, v37
	flat_store_dwordx4 v[154:155], v[148:151] offset:256 sc1
	v_mad_i64_i32 v[154:155], s[2:3], v141, s61, v[152:153]
	s_nop 0
	v_cvt_pk_f16_f32 v148, v30, v31
	v_cvt_pk_f16_f32 v149, v32, v33
	v_cvt_pk_f16_f32 v150, v26, v27
	v_cvt_pk_f16_f32 v151, v28, v29
	v_lshl_add_u64 v[154:155], v[154:155], 0, v[144:145]
	v_add_u32_e32 v141, 0xb0, v140
	flat_store_dwordx4 v[154:155], v[148:151] sc1
	v_mad_i64_i32 v[152:153], s[2:3], v141, s61, v[152:153]
	s_nop 0
	v_cvt_pk_f16_f32 v148, v22, v23
	v_cvt_pk_f16_f32 v149, v24, v25
	v_cvt_pk_f16_f32 v150, v18, v19
	v_cvt_pk_f16_f32 v151, v20, v21
	flat_store_dwordx4 v[154:155], v[148:151] offset:256 sc1
	v_lshl_add_u64 v[144:145], v[152:153], 0, v[144:145]
	s_nop 0
	v_cvt_pk_f16_f32 v148, v14, v15
	v_cvt_pk_f16_f32 v149, v16, v17
	v_cvt_pk_f16_f32 v150, v10, v11
	v_cvt_pk_f16_f32 v151, v12, v13
	flat_store_dwordx4 v[144:145], v[148:151] sc1
	s_nop 1
	v_cvt_pk_f16_f32 v148, v6, v7
	v_cvt_pk_f16_f32 v149, v8, v9
	v_cvt_pk_f16_f32 v150, v2, v3
	v_cvt_pk_f16_f32 v151, v4, v5
	flat_store_dwordx4 v[144:145], v[148:151] offset:256 sc1
	s_cbranch_scc1 .LBB0_903
	v_mul_f32_e32 v127, v127, v127
	v_mul_f32_e32 v123, v123, v123
	v_mul_f32_e32 v119, v119, v119
	v_mul_f32_e32 v115, v115, v115
	v_and_b32_e32 v147, 64, v237
	v_fmac_f32_e32 v127, v126, v126
	v_mul_f32_e32 v126, v129, v129
	v_fmac_f32_e32 v123, v122, v122
	v_mul_f32_e32 v122, v125, v125
	v_fmac_f32_e32 v119, v118, v118
	v_mul_f32_e32 v118, v121, v121
	v_fmac_f32_e32 v115, v114, v114
	v_mul_f32_e32 v114, v117, v117
	s_cmp_eq_u32 s18, 3
	v_xor_b32_e32 v145, 16, v237
	v_add_u32_e32 v147, 64, v147
	v_fmac_f32_e32 v126, v128, v128
	v_fmac_f32_e32 v122, v124, v124
	v_fmac_f32_e32 v118, v120, v120
	v_fmac_f32_e32 v114, v116, v116
	s_cselect_b64 s[2:3], -1, 0
	v_cmp_lt_i32_e32 vcc, v145, v147
	v_add_f32_e32 v126, v127, v126
	v_add_f32_e32 v122, v123, v122
	v_add_f32_e32 v118, v119, v118
	v_add_f32_e32 v114, v115, v114
	v_cndmask_b32_e64 v144, 0, 1.0, s[2:3]
	v_cndmask_b32_e32 v145, v237, v145, vcc
	v_add_f32_e32 v122, v122, v126
	v_add_f32_e32 v114, v114, v118
	v_lshlrev_b32_e32 v145, 2, v145
	v_fmac_f32_e32 v122, v144, v114
	ds_bpermute_b32 v114, v145, v122
	v_xor_b32_e32 v115, 32, v237
	v_cmp_lt_i32_e32 vcc, v115, v147
	s_and_b64 s[2:3], s[2:3], exec
	v_readlane_b32 s2, v255, 8
	v_cndmask_b32_e32 v115, v237, v115, vcc
	v_lshlrev_b32_e32 v116, 2, v115
	s_waitcnt lgkmcnt(0)
	v_add_f32_e32 v117, v122, v114
	ds_bpermute_b32 v118, v116, v117
	v_readlane_b32 s3, v255, 9
	v_ashrrev_i32_e32 v141, 31, v140
	s_cselect_b32 s3, s3, s39
	s_cselect_b32 s2, s2, s38
	v_cmp_eq_u32_e32 vcc, 0, v146
	v_lshl_add_u64 v[114:115], v[140:141], 2, s[2:3]
	s_and_saveexec_b64 s[18:19], vcc
	s_cbranch_execz .LBB0_888
	s_waitcnt lgkmcnt(0)
	v_add_f32_e32 v117, v117, v118
	flat_atomic_add_f32 v[114:115], v117
